# v59 + merge steps: gate loads issued before the last k-step so their latency overlaps the final MFMAs
# baseline (speedup 1.0000x reference)
.LBB0_86:
	s_add_i32 s35, s11, 1
	s_bitcmp1_b32 s35, 0
	s_cselect_b32 s37, 0x9000, 0
	v_add_u32_e32 v110, s37, v81
	v_lshl_add_u64 v[106:107], v[94:95], 0, s[12:13]
	s_mov_b64 s[38:39], 0x6181080
	v_readfirstlane_b32 s37, v110
	v_add_u32_e32 v111, 0x1000, v110
	v_lshl_add_u64 v[108:109], v[106:107], 0, s[38:39]
	s_mov_b32 m0, s37
	s_mov_b64 s[38:39], 0x61e5080
	v_readfirstlane_b32 s37, v111
	v_add_u32_e32 v111, 0x2000, v110
	global_load_lds_dwordx4 v[108:109], off
	v_lshl_add_u64 v[108:109], v[106:107], 0, s[38:39]
	s_mov_b32 m0, s37
	s_mov_b64 s[38:39], 0x6249080
	v_readfirstlane_b32 s37, v111
	v_add_u32_e32 v111, 0x3000, v110
	global_load_lds_dwordx4 v[108:109], off
	v_lshl_add_u64 v[108:109], v[106:107], 0, s[38:39]
	s_mov_b32 m0, s37
	s_mov_b64 s[38:39], 0x62ad080
	v_readfirstlane_b32 s37, v111
	global_load_lds_dwordx4 v[108:109], off
	v_lshl_add_u64 v[108:109], v[106:107], 0, s[38:39]
	s_mov_b32 m0, s37
	s_mov_b64 s[38:39], 0x6311080
	global_load_lds_dwordx4 v[108:109], off
	v_add_u32_e32 v108, 0x4000, v110
	v_lshl_add_u64 v[106:107], v[106:107], 0, s[38:39]
	v_readfirstlane_b32 s37, v108
	s_mov_b32 m0, s37
	v_add_u32_e32 v111, 0x5000, v110
	global_load_lds_dwordx4 v[106:107], off
	v_lshl_add_u64 v[106:107], v[100:101], 0, s[12:13]
	s_mov_b64 s[38:39], 0x14531080
	v_readfirstlane_b32 s37, v111
	v_add_u32_e32 v111, 0x6000, v110
	v_lshl_add_u64 v[108:109], v[106:107], 0, s[38:39]
	s_mov_b32 m0, s37
	s_mov_b64 s[38:39], 0x14541080
	v_readfirstlane_b32 s37, v111
	v_add_u32_e32 v111, 0x7000, v110
	global_load_lds_dwordx4 v[108:109], off
	v_lshl_add_u64 v[108:109], v[106:107], 0, s[38:39]
	s_mov_b32 m0, s37
	s_mov_b64 s[38:39], 0x14551080
	v_readfirstlane_b32 s37, v111
	global_load_lds_dwordx4 v[108:109], off
	v_lshl_add_u64 v[108:109], v[106:107], 0, s[38:39]
	s_mov_b32 m0, s37
	s_mov_b64 s[38:39], 0x14561080
	global_load_lds_dwordx4 v[108:109], off
	v_add_u32_e32 v108, 0x8000, v110
	v_lshl_add_u64 v[106:107], v[106:107], 0, s[38:39]
	v_readfirstlane_b32 s37, v108
	s_mov_b32 m0, s37
	s_bitcmp1_b32 s11, 0
	global_load_lds_dwordx4 v[106:107], off
	s_cselect_b32 s11, 0x9000, 0
	s_add_i32 s11, s11, 0
	v_add_u32_e32 v114, s11, v116
	v_add_u32_e32 v115, v114, v117
	ds_read_b128 v[106:109], v115
	ds_read_b128 v[110:113], v115 offset:2048
	ds_read_b128 v[122:125], v115 offset:4096
	ds_read_b128 v[156:159], v115 offset:6144
	v_add_u32_e32 v114, v114, v118
	ds_read_b128 v[166:169], v115 offset:8192
	ds_read_b128 v[178:181], v114 offset:20480
	ds_read_b128 v[182:185], v114 offset:22528
	ds_read_b128 v[186:189], v114 offset:24576
	ds_read_b128 v[190:193], v114 offset:26624
	v_add_u32_e32 v210, s11, v119
	v_add_u32_e32 v211, v210, v117
	ds_read_b128 v[212:215], v211
	ds_read_b128 v[216:219], v211 offset:2048
	ds_read_b128 v[220:223], v211 offset:4096
	ds_read_b128 v[224:227], v211 offset:6144
	v_add_u32_e32 v228, v210, v118
	ds_read_b128 v[230:233], v211 offset:8192
	ds_read_b128 v[234:237], v228 offset:20480
	ds_read_b128 v[238:241], v228 offset:22528
	ds_read_b128 v[242:245], v228 offset:24576
	ds_read_b128 v[246:249], v228 offset:26624
	s_setprio 1
	s_waitcnt lgkmcnt(9)
	v_mfma_f32_16x16x32_bf16 v[76:79], v[178:181], v[106:109], v[76:79]
	v_mfma_f32_16x16x32_bf16 v[72:75], v[182:185], v[106:109], v[72:75]
	v_mfma_f32_16x16x32_bf16 v[68:71], v[186:189], v[106:109], v[68:71]
	v_mfma_f32_16x16x32_bf16 v[64:67], v[190:193], v[106:109], v[64:67]
	v_mfma_f32_16x16x32_bf16 v[60:63], v[178:181], v[110:113], v[60:63]
	v_mfma_f32_16x16x32_bf16 v[56:59], v[182:185], v[110:113], v[56:59]
	v_mfma_f32_16x16x32_bf16 v[52:55], v[186:189], v[110:113], v[52:55]
	v_mfma_f32_16x16x32_bf16 v[48:51], v[190:193], v[110:113], v[48:51]
	v_mfma_f32_16x16x32_bf16 v[44:47], v[178:181], v[122:125], v[44:47]
	v_mfma_f32_16x16x32_bf16 v[40:43], v[182:185], v[122:125], v[40:43]
	v_mfma_f32_16x16x32_bf16 v[36:39], v[186:189], v[122:125], v[36:39]
	v_mfma_f32_16x16x32_bf16 v[32:35], v[190:193], v[122:125], v[32:35]
	v_mfma_f32_16x16x32_bf16 v[28:31], v[178:181], v[156:159], v[28:31]
	v_mfma_f32_16x16x32_bf16 v[24:27], v[182:185], v[156:159], v[24:27]
	v_mfma_f32_16x16x32_bf16 v[20:23], v[186:189], v[156:159], v[20:23]
	v_mfma_f32_16x16x32_bf16 v[16:19], v[190:193], v[156:159], v[16:19]
	v_mfma_f32_16x16x32_bf16 v[12:15], v[178:181], v[166:169], v[12:15]
	v_mfma_f32_16x16x32_bf16 v[8:11], v[182:185], v[166:169], v[8:11]
	v_mfma_f32_16x16x32_bf16 v[4:7], v[186:189], v[166:169], v[4:7]
	v_mfma_f32_16x16x32_bf16 v[0:3], v[190:193], v[166:169], v[0:3]
	s_setprio 0
	s_setprio 1
	s_waitcnt lgkmcnt(0)
	v_mfma_f32_16x16x32_bf16 v[76:79], v[234:237], v[212:215], v[76:79]
	v_mfma_f32_16x16x32_bf16 v[72:75], v[238:241], v[212:215], v[72:75]
	v_mfma_f32_16x16x32_bf16 v[68:71], v[242:245], v[212:215], v[68:71]
	v_mfma_f32_16x16x32_bf16 v[64:67], v[246:249], v[212:215], v[64:67]
	v_mfma_f32_16x16x32_bf16 v[60:63], v[234:237], v[216:219], v[60:63]
	v_mfma_f32_16x16x32_bf16 v[56:59], v[238:241], v[216:219], v[56:59]
	v_mfma_f32_16x16x32_bf16 v[52:55], v[242:245], v[216:219], v[52:55]
	v_mfma_f32_16x16x32_bf16 v[48:51], v[246:249], v[216:219], v[48:51]
	v_mfma_f32_16x16x32_bf16 v[44:47], v[234:237], v[220:223], v[44:47]
	v_mfma_f32_16x16x32_bf16 v[40:43], v[238:241], v[220:223], v[40:43]
	v_mfma_f32_16x16x32_bf16 v[36:39], v[242:245], v[220:223], v[36:39]
	v_mfma_f32_16x16x32_bf16 v[32:35], v[246:249], v[220:223], v[32:35]
	v_mfma_f32_16x16x32_bf16 v[28:31], v[234:237], v[224:227], v[28:31]
	v_mfma_f32_16x16x32_bf16 v[24:27], v[238:241], v[224:227], v[24:27]
	v_mfma_f32_16x16x32_bf16 v[20:23], v[242:245], v[224:227], v[20:23]
	v_mfma_f32_16x16x32_bf16 v[16:19], v[246:249], v[224:227], v[16:19]
	v_mfma_f32_16x16x32_bf16 v[12:15], v[234:237], v[230:233], v[12:15]
	v_mfma_f32_16x16x32_bf16 v[8:11], v[238:241], v[230:233], v[8:11]
	v_mfma_f32_16x16x32_bf16 v[4:7], v[242:245], v[230:233], v[4:7]
	v_mfma_f32_16x16x32_bf16 v[0:3], v[246:249], v[230:233], v[0:3]
	s_setprio 0
	s_waitcnt vmcnt(0)
	s_add_u32 s12, s12, 0x80
	s_addc_u32 s13, s13, 0
	s_cmpk_lg_i32 s12, 0x780
	s_mov_b32 s11, s35
	s_waitcnt vmcnt(0)
	s_barrier
	s_cbranch_scc1 .LBB0_86
	s_mul_i32 s12, s36, 0xa0
	s_lshl_b32 s13, s10, 7
	v_ashrrev_i32_e32 v242, 7, v176
	v_mov_b32_e32 v243, 0x50
	v_and_or_b32 v248, v176, 15, s12
	v_mad_u32_u24 v248, v242, v243, v248
	v_and_b32_e32 v242, 64, v176
	v_lshrrev_b32_e32 v243, 2, v176
	v_and_b32_e32 v243, 12, v243
	v_or3_b32 v249, v242, v243, s13
	v_mul_u32_u24_e32 v244, 0x3200, v248
	v_lshl_add_u32 v244, v249, 1, v244
	v_add_u32_e32 v244, 0x1800, v244
	v_mov_b32_e32 v247, 0
	v_mov_b32_e32 v246, v244
	v_lshl_add_u64 v[248:249], v[246:247], 0, s[0:1]
	global_load_dwordx2 v[212:213], v[248:249], off
	global_load_dwordx2 v[214:215], v[248:249], off offset:32
	global_load_dwordx2 v[216:217], v[248:249], off offset:64
	global_load_dwordx2 v[218:219], v[248:249], off offset:96
	v_add_u32_e32 v246, 0x32000, v244
	v_lshl_add_u64 v[248:249], v[246:247], 0, s[0:1]
	global_load_dwordx2 v[220:221], v[248:249], off
	global_load_dwordx2 v[222:223], v[248:249], off offset:32
	global_load_dwordx2 v[224:225], v[248:249], off offset:64
	global_load_dwordx2 v[226:227], v[248:249], off offset:96
	v_add_u32_e32 v246, 0x64000, v244
	v_lshl_add_u64 v[248:249], v[246:247], 0, s[0:1]
	global_load_dwordx2 v[202:203], v[248:249], off
	global_load_dwordx2 v[210:211], v[248:249], off offset:32
	global_load_dwordx2 v[230:231], v[248:249], off offset:64
	global_load_dwordx2 v[232:233], v[248:249], off offset:96
	v_add_u32_e32 v246, 0x96000, v244
	v_lshl_add_u64 v[248:249], v[246:247], 0, s[0:1]
	global_load_dwordx2 v[234:235], v[248:249], off
	global_load_dwordx2 v[236:237], v[248:249], off offset:32
	global_load_dwordx2 v[238:239], v[248:249], off offset:64
	global_load_dwordx2 v[240:241], v[248:249], off offset:96
	v_add_u32_e32 v246, 0xc8000, v244
	v_lshl_add_u64 v[248:249], v[246:247], 0, s[0:1]
	global_load_dwordx2 v[242:243], v[248:249], off
	global_load_dwordx2 v[244:245], v[248:249], off offset:32
	global_load_dwordx2 v[246:247], v[248:249], off offset:64
	global_load_dwordx2 v[248:249], v[248:249], off offset:96
	v_add_u32_e32 v122, v120, v118
	v_add_u32_e32 v123, v120, v117
	ds_read_b128 v[106:109], v122 offset:63488
	ds_read_b128 v[110:113], v122 offset:61440
	ds_read_b128 v[156:159], v122 offset:59392
	ds_read_b128 v[166:169], v122 offset:57344
	ds_read_b128 v[178:181], v123 offset:45056
	ds_read_b128 v[182:185], v123 offset:43008
	ds_read_b128 v[186:189], v123 offset:40960
	ds_read_b128 v[190:193], v123 offset:38912
	ds_read_b128 v[194:197], v123 offset:36864
	s_setprio 1
	s_waitcnt lgkmcnt(0)
	v_mfma_f32_16x16x32_bf16 v[76:79], v[166:169], v[194:197], v[76:79]
	v_mfma_f32_16x16x32_bf16 v[72:75], v[156:159], v[194:197], v[72:75]
	v_mfma_f32_16x16x32_bf16 v[68:71], v[110:113], v[194:197], v[68:71]
	v_mfma_f32_16x16x32_bf16 v[64:67], v[106:109], v[194:197], v[64:67]
	v_mfma_f32_16x16x32_bf16 v[60:63], v[166:169], v[190:193], v[60:63]
	v_mfma_f32_16x16x32_bf16 v[56:59], v[156:159], v[190:193], v[56:59]
	v_mfma_f32_16x16x32_bf16 v[52:55], v[110:113], v[190:193], v[52:55]
	v_mfma_f32_16x16x32_bf16 v[48:51], v[106:109], v[190:193], v[48:51]
	v_mfma_f32_16x16x32_bf16 v[44:47], v[166:169], v[186:189], v[44:47]
	v_mfma_f32_16x16x32_bf16 v[40:43], v[156:159], v[186:189], v[40:43]
	v_mfma_f32_16x16x32_bf16 v[36:39], v[110:113], v[186:189], v[36:39]
	v_mfma_f32_16x16x32_bf16 v[32:35], v[106:109], v[186:189], v[32:35]
	v_mfma_f32_16x16x32_bf16 v[28:31], v[166:169], v[182:185], v[28:31]
	v_mfma_f32_16x16x32_bf16 v[24:27], v[156:159], v[182:185], v[24:27]
	v_mfma_f32_16x16x32_bf16 v[20:23], v[110:113], v[182:185], v[20:23]
	v_mfma_f32_16x16x32_bf16 v[16:19], v[106:109], v[182:185], v[16:19]
	v_mfma_f32_16x16x32_bf16 v[12:15], v[166:169], v[178:181], v[12:15]
	v_mfma_f32_16x16x32_bf16 v[8:11], v[156:159], v[178:181], v[8:11]
	v_mfma_f32_16x16x32_bf16 v[4:7], v[110:113], v[178:181], v[4:7]
	v_mfma_f32_16x16x32_bf16 v[0:3], v[106:109], v[178:181], v[0:3]
	s_setprio 0
	v_add_u32_e32 v124, v121, v117
	ds_read_b128 v[106:109], v124 offset:36864
	ds_read_b128 v[110:113], v124 offset:38912
	ds_read_b128 v[156:159], v124 offset:40960
	ds_read_b128 v[166:169], v124 offset:43008
	v_add_u32_e32 v125, v121, v118
	ds_read_b128 v[178:181], v124 offset:45056
	ds_read_b128 v[182:185], v125 offset:57344
	ds_read_b128 v[186:189], v125 offset:59392
	ds_read_b128 v[190:193], v125 offset:61440
	ds_read_b128 v[194:197], v125 offset:63488
	s_setprio 1
	s_waitcnt lgkmcnt(1)
	v_mfma_f32_16x16x32_bf16 v[68:71], v[190:193], v[106:109], v[68:71]
	s_waitcnt lgkmcnt(0)
	v_mfma_f32_16x16x32_bf16 v[64:67], v[194:197], v[106:109], v[64:67]
	v_mfma_f32_16x16x32_bf16 v[60:63], v[182:185], v[110:113], v[60:63]
	v_mfma_f32_16x16x32_bf16 v[56:59], v[186:189], v[110:113], v[56:59]
	v_mfma_f32_16x16x32_bf16 v[52:55], v[190:193], v[110:113], v[52:55]
	v_mfma_f32_16x16x32_bf16 v[48:51], v[194:197], v[110:113], v[48:51]
	v_mfma_f32_16x16x32_bf16 v[44:47], v[182:185], v[156:159], v[44:47]
	v_mfma_f32_16x16x32_bf16 v[40:43], v[186:189], v[156:159], v[40:43]
	v_mfma_f32_16x16x32_bf16 v[36:39], v[190:193], v[156:159], v[36:39]
	v_mfma_f32_16x16x32_bf16 v[32:35], v[194:197], v[156:159], v[32:35]
	v_mfma_f32_16x16x32_bf16 v[28:31], v[182:185], v[166:169], v[28:31]
	v_mfma_f32_16x16x32_bf16 v[24:27], v[186:189], v[166:169], v[24:27]
	v_mfma_f32_16x16x32_bf16 v[20:23], v[190:193], v[166:169], v[20:23]
	v_mfma_f32_16x16x32_bf16 v[16:19], v[194:197], v[166:169], v[16:19]
	v_mfma_f32_16x16x32_bf16 v[12:15], v[182:185], v[178:181], v[12:15]
	v_mfma_f32_16x16x32_bf16 v[8:11], v[186:189], v[178:181], v[8:11]
	v_mfma_f32_16x16x32_bf16 v[4:7], v[190:193], v[178:181], v[4:7]
	v_mfma_f32_16x16x32_bf16 v[0:3], v[194:197], v[178:181], v[0:3]
	v_mfma_f32_16x16x32_bf16 v[198:201], v[182:185], v[106:109], v[76:79]
	v_mfma_f32_16x16x32_bf16 v[206:209], v[186:189], v[106:109], v[72:75]
	s_setprio 0
	s_nop 1
	v_mov_b32_e32 v72, v97
	s_waitcnt vmcnt(0)
	s_barrier
	s_mul_i32 s12, s36, 0xa0
	s_movk_i32 s11, 0x50
	s_mov_b32 s35, 0
	s_lshl_b32 s13, s10, 7
	s_movk_i32 s36, 0x3200
	s_mov_b64 s[38:39], 0x1800
	s_mov_b64 s[10:11], 0x800
	v_ashrrev_i32_e32 v190, 7, v176
	v_mov_b32_e32 v191, 0x50
	v_and_or_b32 v194, v176, 15, s12
	v_mad_u32_u24 v194, v190, v191, v194
	v_and_b32_e32 v190, 64, v176
	v_lshrrev_b32_e32 v191, 2, v176
	v_and_b32_e32 v191, 12, v191
	v_or3_b32 v195, v190, v191, s13
	v_lshlrev_b32_e32 v192, 12, v194
	v_lshl_add_u32 v192, v195, 2, v192
	v_mov_b32_e32 v115, 0
	v_mov_b32_e32 v114, v192
	v_lshl_add_u64 v[196:197], v[114:115], 0, s[4:5]
	v_lshlrev_b32_e32 v190, 16, v212
	v_and_b32_e32 v191, 0xffff0000, v212
	v_pk_mul_f32 v[198:199], v[198:199], v[190:191]
	v_lshlrev_b32_e32 v212, 16, v213
	v_and_b32_e32 v213, 0xffff0000, v213
	v_pk_mul_f32 v[200:201], v[200:201], v[212:213]
	s_nop 0
	global_store_dwordx4 v[196:197], v[198:201], off
	v_lshlrev_b32_e32 v190, 16, v214
	v_and_b32_e32 v191, 0xffff0000, v214
	v_pk_mul_f32 v[206:207], v[206:207], v[190:191]
	v_lshlrev_b32_e32 v214, 16, v215
	v_and_b32_e32 v215, 0xffff0000, v215
	v_pk_mul_f32 v[208:209], v[208:209], v[214:215]
	s_nop 0
	global_store_dwordx4 v[196:197], v[206:209], off offset:64
	v_lshlrev_b32_e32 v190, 16, v216
	v_and_b32_e32 v191, 0xffff0000, v216
	v_pk_mul_f32 v[68:69], v[68:69], v[190:191]
	v_lshlrev_b32_e32 v216, 16, v217
	v_and_b32_e32 v217, 0xffff0000, v217
	v_pk_mul_f32 v[70:71], v[70:71], v[216:217]
	s_nop 0
	global_store_dwordx4 v[196:197], v[68:71], off offset:128
	v_lshlrev_b32_e32 v190, 16, v218
	v_and_b32_e32 v191, 0xffff0000, v218
	v_pk_mul_f32 v[64:65], v[64:65], v[190:191]
	v_lshlrev_b32_e32 v218, 16, v219
	v_and_b32_e32 v219, 0xffff0000, v219
	v_pk_mul_f32 v[66:67], v[66:67], v[218:219]
	s_nop 0
	global_store_dwordx4 v[196:197], v[64:67], off offset:192
	v_add_u32_e32 v114, 0x10000, v192
	v_lshl_add_u64 v[196:197], v[114:115], 0, s[4:5]
	v_lshlrev_b32_e32 v190, 16, v220
	v_and_b32_e32 v191, 0xffff0000, v220
	v_pk_mul_f32 v[60:61], v[60:61], v[190:191]
	v_lshlrev_b32_e32 v220, 16, v221
	v_and_b32_e32 v221, 0xffff0000, v221
	v_pk_mul_f32 v[62:63], v[62:63], v[220:221]
	s_nop 0
	global_store_dwordx4 v[196:197], v[60:63], off
	v_lshlrev_b32_e32 v190, 16, v222
	v_and_b32_e32 v191, 0xffff0000, v222
	v_pk_mul_f32 v[56:57], v[56:57], v[190:191]
	v_lshlrev_b32_e32 v222, 16, v223
	v_and_b32_e32 v223, 0xffff0000, v223
	v_pk_mul_f32 v[58:59], v[58:59], v[222:223]
	s_nop 0
	global_store_dwordx4 v[196:197], v[56:59], off offset:64
	v_lshlrev_b32_e32 v190, 16, v224
	v_and_b32_e32 v191, 0xffff0000, v224
	v_pk_mul_f32 v[52:53], v[52:53], v[190:191]
	v_lshlrev_b32_e32 v224, 16, v225
	v_and_b32_e32 v225, 0xffff0000, v225
	v_pk_mul_f32 v[54:55], v[54:55], v[224:225]
	s_nop 0
	global_store_dwordx4 v[196:197], v[52:55], off offset:128
	v_lshlrev_b32_e32 v190, 16, v226
	v_and_b32_e32 v191, 0xffff0000, v226
	v_pk_mul_f32 v[48:49], v[48:49], v[190:191]
	v_lshlrev_b32_e32 v226, 16, v227
	v_and_b32_e32 v227, 0xffff0000, v227
	v_pk_mul_f32 v[50:51], v[50:51], v[226:227]
	s_nop 0
	global_store_dwordx4 v[196:197], v[48:51], off offset:192
	v_add_u32_e32 v114, 0x20000, v192
	v_lshl_add_u64 v[196:197], v[114:115], 0, s[4:5]
	v_lshlrev_b32_e32 v190, 16, v202
	v_and_b32_e32 v191, 0xffff0000, v202
	v_pk_mul_f32 v[44:45], v[44:45], v[190:191]
	v_lshlrev_b32_e32 v202, 16, v203
	v_and_b32_e32 v203, 0xffff0000, v203
	v_pk_mul_f32 v[46:47], v[46:47], v[202:203]
	s_nop 0
	global_store_dwordx4 v[196:197], v[44:47], off
	v_lshlrev_b32_e32 v190, 16, v210
	v_and_b32_e32 v191, 0xffff0000, v210
	v_pk_mul_f32 v[40:41], v[40:41], v[190:191]
	v_lshlrev_b32_e32 v210, 16, v211
	v_and_b32_e32 v211, 0xffff0000, v211
	v_pk_mul_f32 v[42:43], v[42:43], v[210:211]
	s_nop 0
	global_store_dwordx4 v[196:197], v[40:43], off offset:64
	v_lshlrev_b32_e32 v190, 16, v230
	v_and_b32_e32 v191, 0xffff0000, v230
	v_pk_mul_f32 v[36:37], v[36:37], v[190:191]
	v_lshlrev_b32_e32 v230, 16, v231
	v_and_b32_e32 v231, 0xffff0000, v231
	v_pk_mul_f32 v[38:39], v[38:39], v[230:231]
	s_nop 0
	global_store_dwordx4 v[196:197], v[36:39], off offset:128
	v_lshlrev_b32_e32 v190, 16, v232
	v_and_b32_e32 v191, 0xffff0000, v232
	v_pk_mul_f32 v[32:33], v[32:33], v[190:191]
	v_lshlrev_b32_e32 v232, 16, v233
	v_and_b32_e32 v233, 0xffff0000, v233
	v_pk_mul_f32 v[34:35], v[34:35], v[232:233]
	s_nop 0
	global_store_dwordx4 v[196:197], v[32:35], off offset:192
	v_add_u32_e32 v114, 0x30000, v192
	v_lshl_add_u64 v[196:197], v[114:115], 0, s[4:5]
	v_lshlrev_b32_e32 v190, 16, v234
	v_and_b32_e32 v191, 0xffff0000, v234
	v_pk_mul_f32 v[28:29], v[28:29], v[190:191]
	v_lshlrev_b32_e32 v234, 16, v235
	v_and_b32_e32 v235, 0xffff0000, v235
	v_pk_mul_f32 v[30:31], v[30:31], v[234:235]
	s_nop 0
	global_store_dwordx4 v[196:197], v[28:31], off
	v_lshlrev_b32_e32 v190, 16, v236
	v_and_b32_e32 v191, 0xffff0000, v236
	v_pk_mul_f32 v[24:25], v[24:25], v[190:191]
	v_lshlrev_b32_e32 v236, 16, v237
	v_and_b32_e32 v237, 0xffff0000, v237
	v_pk_mul_f32 v[26:27], v[26:27], v[236:237]
	s_nop 0
	global_store_dwordx4 v[196:197], v[24:27], off offset:64
	v_lshlrev_b32_e32 v190, 16, v238
	v_and_b32_e32 v191, 0xffff0000, v238
	v_pk_mul_f32 v[20:21], v[20:21], v[190:191]
	v_lshlrev_b32_e32 v238, 16, v239
	v_and_b32_e32 v239, 0xffff0000, v239
	v_pk_mul_f32 v[22:23], v[22:23], v[238:239]
	s_nop 0
	global_store_dwordx4 v[196:197], v[20:23], off offset:128
	v_lshlrev_b32_e32 v190, 16, v240
	v_and_b32_e32 v191, 0xffff0000, v240
	v_pk_mul_f32 v[16:17], v[16:17], v[190:191]
	v_lshlrev_b32_e32 v240, 16, v241
	v_and_b32_e32 v241, 0xffff0000, v241
	v_pk_mul_f32 v[18:19], v[18:19], v[240:241]
	s_nop 0
	global_store_dwordx4 v[196:197], v[16:19], off offset:192
	v_add_u32_e32 v114, 0x40000, v192
	v_lshl_add_u64 v[196:197], v[114:115], 0, s[4:5]
	v_lshlrev_b32_e32 v190, 16, v242
	v_and_b32_e32 v191, 0xffff0000, v242
	v_pk_mul_f32 v[12:13], v[12:13], v[190:191]
	v_lshlrev_b32_e32 v242, 16, v243
	v_and_b32_e32 v243, 0xffff0000, v243
	v_pk_mul_f32 v[14:15], v[14:15], v[242:243]
	s_nop 0
	global_store_dwordx4 v[196:197], v[12:15], off
	v_lshlrev_b32_e32 v190, 16, v244
	v_and_b32_e32 v191, 0xffff0000, v244
	v_pk_mul_f32 v[8:9], v[8:9], v[190:191]
	v_lshlrev_b32_e32 v244, 16, v245
	v_and_b32_e32 v245, 0xffff0000, v245
	v_pk_mul_f32 v[10:11], v[10:11], v[244:245]
	s_nop 0
	global_store_dwordx4 v[196:197], v[8:11], off offset:64
	v_lshlrev_b32_e32 v190, 16, v246
	v_and_b32_e32 v191, 0xffff0000, v246
	v_pk_mul_f32 v[4:5], v[4:5], v[190:191]
	v_lshlrev_b32_e32 v246, 16, v247
	v_and_b32_e32 v247, 0xffff0000, v247
	v_pk_mul_f32 v[6:7], v[6:7], v[246:247]
	s_nop 0
	global_store_dwordx4 v[196:197], v[4:7], off offset:128
	v_lshlrev_b32_e32 v190, 16, v248
	v_and_b32_e32 v191, 0xffff0000, v248
	v_pk_mul_f32 v[0:1], v[0:1], v[190:191]
	v_lshlrev_b32_e32 v248, 16, v249
	v_and_b32_e32 v249, 0xffff0000, v249
	v_pk_mul_f32 v[2:3], v[2:3], v[248:249]
	s_nop 0
	global_store_dwordx4 v[196:197], v[0:3], off offset:192
	s_nop 1
	v_lshl_add_u64 v[0:1], v[104:105], 0, s[10:11]
	v_readfirstlane_b32 s10, v81
	s_mov_b32 m0, s10
	s_mov_b64 s[10:11], 0x64800
	global_load_lds_dwordx4 v[0:1], off
	v_lshl_add_u64 v[0:1], v[104:105], 0, s[10:11]
	v_readfirstlane_b32 s10, v133
	s_mov_b32 m0, s10
	s_mov_b64 s[10:11], 0xc8800
	global_load_lds_dwordx4 v[0:1], off
	v_lshl_add_u64 v[0:1], v[104:105], 0, s[10:11]
	v_readfirstlane_b32 s10, v132
	s_mov_b32 m0, s10
	s_mov_b64 s[10:11], 0x12c800
	global_load_lds_dwordx4 v[0:1], off
	v_lshl_add_u64 v[0:1], v[104:105], 0, s[10:11]
	v_readfirstlane_b32 s10, v131
	s_mov_b32 m0, s10
	s_mov_b64 s[10:11], 0x190800
	global_load_lds_dwordx4 v[0:1], off
	v_lshl_add_u64 v[0:1], v[104:105], 0, s[10:11]
	v_readfirstlane_b32 s10, v130
	s_mov_b32 m0, s10
	v_readfirstlane_b32 s10, v129
	global_load_lds_dwordx4 v[0:1], off
	v_lshl_add_u64 v[0:1], v[86:87], 0, s[8:9]
	s_mov_b32 m0, s10
	v_readfirstlane_b32 s10, v128
	global_load_lds_dwordx4 v[0:1], off
	v_lshl_add_u64 v[2:3], v[0:1], 0, s[40:41]
	s_mov_b32 m0, s10
	s_mov_b64 s[10:11], 0x20000
	global_load_lds_dwordx4 v[2:3], off
	v_lshl_add_u64 v[2:3], v[0:1], 0, s[10:11]
	v_readfirstlane_b32 s10, v127
	s_mov_b32 m0, s10
	s_mov_b64 s[10:11], 0x30000
	v_lshl_add_u64 v[0:1], v[0:1], 0, s[10:11]
	v_readfirstlane_b32 s10, v126
	global_load_lds_dwordx4 v[2:3], off
	s_mov_b32 m0, s10
	s_mov_b64 s[10:11], 0
	global_load_lds_dwordx4 v[0:1], off
	s_waitcnt vmcnt(0)
	v_mov_b32_e32 v0, 0
	v_mov_b32_e32 v1, v0
	v_mov_b32_e32 v2, v0
	v_mov_b32_e32 v3, v0
	v_mov_b32_e32 v4, v0
	v_mov_b32_e32 v5, v0
	v_mov_b32_e32 v6, v0
	v_mov_b32_e32 v7, v0
	v_mov_b32_e32 v8, v0
	v_mov_b32_e32 v9, v0
	v_mov_b32_e32 v10, v0
	v_mov_b32_e32 v11, v0
	v_mov_b32_e32 v12, v0
	v_mov_b32_e32 v13, v0
	v_mov_b32_e32 v14, v0
	v_mov_b32_e32 v15, v0
	v_mov_b32_e32 v16, v0
	v_mov_b32_e32 v17, v0
	v_mov_b32_e32 v18, v0
	v_mov_b32_e32 v19, v0
	v_mov_b32_e32 v20, v0
	v_mov_b32_e32 v21, v0
	v_mov_b32_e32 v22, v0
	v_mov_b32_e32 v23, v0
	v_mov_b32_e32 v24, v0
	v_mov_b32_e32 v25, v0
	v_mov_b32_e32 v26, v0
	v_mov_b32_e32 v27, v0
	v_mov_b32_e32 v28, v0
	v_mov_b32_e32 v29, v0
	v_mov_b32_e32 v30, v0
	v_mov_b32_e32 v31, v0
	v_mov_b32_e32 v32, v0
	v_mov_b32_e32 v33, v0
	v_mov_b32_e32 v34, v0
	v_mov_b32_e32 v35, v0
	v_mov_b32_e32 v36, v0
	v_mov_b32_e32 v37, v0
	v_mov_b32_e32 v38, v0
	v_mov_b32_e32 v39, v0
	v_mov_b32_e32 v40, v0
	v_mov_b32_e32 v41, v0
	v_mov_b32_e32 v42, v0
	v_mov_b32_e32 v43, v0
	v_mov_b32_e32 v44, v0
	v_mov_b32_e32 v45, v0
	v_mov_b32_e32 v46, v0
	v_mov_b32_e32 v47, v0
	v_mov_b32_e32 v48, v0
	v_mov_b32_e32 v49, v0
	v_mov_b32_e32 v50, v0
	v_mov_b32_e32 v51, v0
	v_mov_b32_e32 v52, v0
	v_mov_b32_e32 v53, v0
	v_mov_b32_e32 v54, v0
	v_mov_b32_e32 v55, v0
	v_mov_b32_e32 v56, v0
	v_mov_b32_e32 v57, v0
	v_mov_b32_e32 v58, v0
	v_mov_b32_e32 v59, v0
	v_mov_b32_e32 v60, v0
	v_mov_b32_e32 v61, v0
	v_mov_b32_e32 v62, v0
	v_mov_b32_e32 v63, v0
	v_mov_b32_e32 v64, v0
	v_mov_b32_e32 v65, v0
	v_mov_b32_e32 v66, v0
	v_mov_b32_e32 v67, v0
	v_mov_b32_e32 v68, v0
	v_mov_b32_e32 v69, v0
	v_mov_b32_e32 v70, v0
	v_mov_b32_e32 v71, v0
	v_mov_b32_e32 v72, v0
	v_mov_b32_e32 v73, v0
	v_mov_b32_e32 v74, v0
	v_mov_b32_e32 v75, v0
	v_mov_b32_e32 v76, v0
	v_mov_b32_e32 v77, v0
	v_mov_b32_e32 v78, v0
	v_mov_b32_e32 v79, v0
	s_waitcnt vmcnt(0) lgkmcnt(0)
	s_barrier
.LBB0_88:
	s_add_i32 s36, s35, 1
	s_bitcmp1_b32 s36, 0
	s_cselect_b32 s37, 0x9000, 0
	v_add_u32_e32 v108, s37, v81
	v_lshl_add_u64 v[104:105], v[94:95], 0, s[10:11]
	s_mov_b64 s[38:39], 0x6181880
	v_readfirstlane_b32 s37, v108
	v_add_u32_e32 v109, 0x1000, v108
	v_lshl_add_u64 v[106:107], v[104:105], 0, s[38:39]
	s_mov_b32 m0, s37
	s_mov_b64 s[38:39], 0x61e5880
	v_readfirstlane_b32 s37, v109
	v_add_u32_e32 v109, 0x2000, v108
	global_load_lds_dwordx4 v[106:107], off
	v_lshl_add_u64 v[106:107], v[104:105], 0, s[38:39]
	s_mov_b32 m0, s37
	s_mov_b64 s[38:39], 0x6249880
	v_readfirstlane_b32 s37, v109
	v_add_u32_e32 v109, 0x3000, v108
	global_load_lds_dwordx4 v[106:107], off
	v_lshl_add_u64 v[106:107], v[104:105], 0, s[38:39]
	s_mov_b32 m0, s37
	s_mov_b64 s[38:39], 0x62ad880
	v_readfirstlane_b32 s37, v109
	global_load_lds_dwordx4 v[106:107], off
	v_lshl_add_u64 v[106:107], v[104:105], 0, s[38:39]
	s_mov_b32 m0, s37
	s_mov_b64 s[38:39], 0x6311880
	global_load_lds_dwordx4 v[106:107], off
	v_add_u32_e32 v106, 0x4000, v108
	v_lshl_add_u64 v[104:105], v[104:105], 0, s[38:39]
	v_readfirstlane_b32 s37, v106
	s_mov_b32 m0, s37
	v_add_u32_e32 v109, 0x5000, v108
	global_load_lds_dwordx4 v[104:105], off
	v_lshl_add_u64 v[104:105], v[100:101], 0, s[10:11]
	s_mov_b64 s[38:39], 0x14731080
	v_readfirstlane_b32 s37, v109
	v_add_u32_e32 v109, 0x6000, v108
	v_lshl_add_u64 v[106:107], v[104:105], 0, s[38:39]
	s_mov_b32 m0, s37
	s_mov_b64 s[38:39], 0x14741080
	v_readfirstlane_b32 s37, v109
	v_add_u32_e32 v109, 0x7000, v108
	global_load_lds_dwordx4 v[106:107], off
	v_lshl_add_u64 v[106:107], v[104:105], 0, s[38:39]
	s_mov_b32 m0, s37
	s_mov_b64 s[38:39], 0x14751080
	v_readfirstlane_b32 s37, v109
	global_load_lds_dwordx4 v[106:107], off
	v_lshl_add_u64 v[106:107], v[104:105], 0, s[38:39]
	s_mov_b32 m0, s37
	s_mov_b64 s[38:39], 0x14761080
	global_load_lds_dwordx4 v[106:107], off
	v_add_u32_e32 v106, 0x8000, v108
	v_lshl_add_u64 v[104:105], v[104:105], 0, s[38:39]
	v_readfirstlane_b32 s37, v106
	s_mov_b32 m0, s37
	s_bitcmp1_b32 s35, 0
	global_load_lds_dwordx4 v[104:105], off
	s_cselect_b32 s35, 0x9000, 0
	s_add_i32 s35, s35, 0
	v_add_u32_e32 v166, s35, v116
	v_add_u32_e32 v167, v166, v117
	ds_read_b128 v[104:107], v167
	ds_read_b128 v[108:111], v167 offset:2048
	ds_read_b128 v[112:115], v167 offset:4096
	ds_read_b128 v[156:159], v167 offset:6144
	v_add_u32_e32 v177, v166, v118
	ds_read_b128 v[166:169], v167 offset:8192
	ds_read_b128 v[178:181], v177 offset:20480
	ds_read_b128 v[182:185], v177 offset:22528
	ds_read_b128 v[186:189], v177 offset:24576
	ds_read_b128 v[190:193], v177 offset:26624
	v_add_u32_e32 v210, s35, v119
	v_add_u32_e32 v211, v210, v117
	ds_read_b128 v[212:215], v211
	ds_read_b128 v[216:219], v211 offset:2048
	ds_read_b128 v[220:223], v211 offset:4096
	ds_read_b128 v[224:227], v211 offset:6144
	v_add_u32_e32 v228, v210, v118
	ds_read_b128 v[230:233], v211 offset:8192
	ds_read_b128 v[234:237], v228 offset:20480
	ds_read_b128 v[238:241], v228 offset:22528
	ds_read_b128 v[242:245], v228 offset:24576
	ds_read_b128 v[246:249], v228 offset:26624
	s_setprio 1
	s_waitcnt lgkmcnt(9)
	v_mfma_f32_16x16x32_bf16 v[76:79], v[178:181], v[104:107], v[76:79]
	v_mfma_f32_16x16x32_bf16 v[72:75], v[182:185], v[104:107], v[72:75]
	v_mfma_f32_16x16x32_bf16 v[68:71], v[186:189], v[104:107], v[68:71]
	v_mfma_f32_16x16x32_bf16 v[64:67], v[190:193], v[104:107], v[64:67]
	v_mfma_f32_16x16x32_bf16 v[60:63], v[178:181], v[108:111], v[60:63]
	v_mfma_f32_16x16x32_bf16 v[56:59], v[182:185], v[108:111], v[56:59]
	v_mfma_f32_16x16x32_bf16 v[52:55], v[186:189], v[108:111], v[52:55]
	v_mfma_f32_16x16x32_bf16 v[48:51], v[190:193], v[108:111], v[48:51]
	v_mfma_f32_16x16x32_bf16 v[44:47], v[178:181], v[112:115], v[44:47]
	v_mfma_f32_16x16x32_bf16 v[40:43], v[182:185], v[112:115], v[40:43]
	v_mfma_f32_16x16x32_bf16 v[36:39], v[186:189], v[112:115], v[36:39]
	v_mfma_f32_16x16x32_bf16 v[32:35], v[190:193], v[112:115], v[32:35]
	v_mfma_f32_16x16x32_bf16 v[28:31], v[178:181], v[156:159], v[28:31]
	v_mfma_f32_16x16x32_bf16 v[24:27], v[182:185], v[156:159], v[24:27]
	v_mfma_f32_16x16x32_bf16 v[20:23], v[186:189], v[156:159], v[20:23]
	v_mfma_f32_16x16x32_bf16 v[16:19], v[190:193], v[156:159], v[16:19]
	v_mfma_f32_16x16x32_bf16 v[12:15], v[178:181], v[166:169], v[12:15]
	v_mfma_f32_16x16x32_bf16 v[8:11], v[182:185], v[166:169], v[8:11]
	v_mfma_f32_16x16x32_bf16 v[4:7], v[186:189], v[166:169], v[4:7]
	v_mfma_f32_16x16x32_bf16 v[0:3], v[190:193], v[166:169], v[0:3]
	s_setprio 0
	s_setprio 1
	s_waitcnt lgkmcnt(0)
	v_mfma_f32_16x16x32_bf16 v[76:79], v[234:237], v[212:215], v[76:79]
	v_mfma_f32_16x16x32_bf16 v[72:75], v[238:241], v[212:215], v[72:75]
	v_mfma_f32_16x16x32_bf16 v[68:71], v[242:245], v[212:215], v[68:71]
	v_mfma_f32_16x16x32_bf16 v[64:67], v[246:249], v[212:215], v[64:67]
	v_mfma_f32_16x16x32_bf16 v[60:63], v[234:237], v[216:219], v[60:63]
	v_mfma_f32_16x16x32_bf16 v[56:59], v[238:241], v[216:219], v[56:59]
	v_mfma_f32_16x16x32_bf16 v[52:55], v[242:245], v[216:219], v[52:55]
	v_mfma_f32_16x16x32_bf16 v[48:51], v[246:249], v[216:219], v[48:51]
	v_mfma_f32_16x16x32_bf16 v[44:47], v[234:237], v[220:223], v[44:47]
	v_mfma_f32_16x16x32_bf16 v[40:43], v[238:241], v[220:223], v[40:43]
	v_mfma_f32_16x16x32_bf16 v[36:39], v[242:245], v[220:223], v[36:39]
	v_mfma_f32_16x16x32_bf16 v[32:35], v[246:249], v[220:223], v[32:35]
	v_mfma_f32_16x16x32_bf16 v[28:31], v[234:237], v[224:227], v[28:31]
	v_mfma_f32_16x16x32_bf16 v[24:27], v[238:241], v[224:227], v[24:27]
	v_mfma_f32_16x16x32_bf16 v[20:23], v[242:245], v[224:227], v[20:23]
	v_mfma_f32_16x16x32_bf16 v[16:19], v[246:249], v[224:227], v[16:19]
	v_mfma_f32_16x16x32_bf16 v[12:15], v[234:237], v[230:233], v[12:15]
	v_mfma_f32_16x16x32_bf16 v[8:11], v[238:241], v[230:233], v[8:11]
	v_mfma_f32_16x16x32_bf16 v[4:7], v[242:245], v[230:233], v[4:7]
	v_mfma_f32_16x16x32_bf16 v[0:3], v[246:249], v[230:233], v[0:3]
	s_setprio 0
	s_waitcnt vmcnt(0)
	s_add_u32 s10, s10, 0x80
	s_addc_u32 s11, s11, 0
	s_cmpk_lg_i32 s10, 0x780
	s_mov_b32 s35, s36
	s_waitcnt vmcnt(0)
	s_barrier
	s_cbranch_scc1 .LBB0_88
	v_ashrrev_i32_e32 v242, 7, v176
	v_mov_b32_e32 v243, 0x50
	v_and_or_b32 v248, v176, 15, s12
	v_mad_u32_u24 v248, v242, v243, v248
	v_and_b32_e32 v242, 64, v176
	v_lshrrev_b32_e32 v243, 2, v176
	v_and_b32_e32 v243, 12, v243
	v_or3_b32 v249, v242, v243, s13
	v_mul_u32_u24_e32 v244, 0x3200, v248
	v_lshl_add_u32 v244, v249, 1, v244
	v_add_u32_e32 v244, 0x2000, v244
	v_mov_b32_e32 v247, 0
	v_mov_b32_e32 v246, v244
	v_lshl_add_u64 v[248:249], v[246:247], 0, s[0:1]
	global_load_dwordx2 v[212:213], v[248:249], off
	global_load_dwordx2 v[214:215], v[248:249], off offset:32
	global_load_dwordx2 v[216:217], v[248:249], off offset:64
	global_load_dwordx2 v[218:219], v[248:249], off offset:96
	v_add_u32_e32 v246, 0x32000, v244
	v_lshl_add_u64 v[248:249], v[246:247], 0, s[0:1]
	global_load_dwordx2 v[220:221], v[248:249], off
	global_load_dwordx2 v[222:223], v[248:249], off offset:32
	global_load_dwordx2 v[224:225], v[248:249], off offset:64
	global_load_dwordx2 v[226:227], v[248:249], off offset:96
	v_add_u32_e32 v246, 0x64000, v244
	v_lshl_add_u64 v[248:249], v[246:247], 0, s[0:1]
	global_load_dwordx2 v[202:203], v[248:249], off
	global_load_dwordx2 v[210:211], v[248:249], off offset:32
	global_load_dwordx2 v[230:231], v[248:249], off offset:64
	global_load_dwordx2 v[232:233], v[248:249], off offset:96
	v_add_u32_e32 v246, 0x96000, v244
	v_lshl_add_u64 v[248:249], v[246:247], 0, s[0:1]
	global_load_dwordx2 v[234:235], v[248:249], off
	global_load_dwordx2 v[236:237], v[248:249], off offset:32
	global_load_dwordx2 v[238:239], v[248:249], off offset:64
	global_load_dwordx2 v[240:241], v[248:249], off offset:96
	v_add_u32_e32 v246, 0xc8000, v244
	v_lshl_add_u64 v[248:249], v[246:247], 0, s[0:1]
	global_load_dwordx2 v[242:243], v[248:249], off
	global_load_dwordx2 v[244:245], v[248:249], off offset:32
	global_load_dwordx2 v[246:247], v[248:249], off offset:64
	global_load_dwordx2 v[248:249], v[248:249], off offset:96
	ds_read_b128 v[104:107], v122 offset:63488
	ds_read_b128 v[108:111], v122 offset:61440
	ds_read_b128 v[112:115], v122 offset:59392
	ds_read_b128 v[156:159], v122 offset:57344
	ds_read_b128 v[166:169], v123 offset:45056
	ds_read_b128 v[178:181], v123 offset:43008
	ds_read_b128 v[182:185], v123 offset:40960
	ds_read_b128 v[186:189], v123 offset:38912
	ds_read_b128 v[190:193], v123 offset:36864
	s_setprio 1
	s_waitcnt lgkmcnt(0)
	v_mfma_f32_16x16x32_bf16 v[76:79], v[156:159], v[190:193], v[76:79]
	v_mfma_f32_16x16x32_bf16 v[72:75], v[112:115], v[190:193], v[72:75]
	v_mfma_f32_16x16x32_bf16 v[68:71], v[108:111], v[190:193], v[68:71]
	v_mfma_f32_16x16x32_bf16 v[64:67], v[104:107], v[190:193], v[64:67]
	v_mfma_f32_16x16x32_bf16 v[60:63], v[156:159], v[186:189], v[60:63]
	v_mfma_f32_16x16x32_bf16 v[56:59], v[112:115], v[186:189], v[56:59]
	v_mfma_f32_16x16x32_bf16 v[52:55], v[108:111], v[186:189], v[52:55]
	v_mfma_f32_16x16x32_bf16 v[48:51], v[104:107], v[186:189], v[48:51]
	v_mfma_f32_16x16x32_bf16 v[44:47], v[156:159], v[182:185], v[44:47]
	v_mfma_f32_16x16x32_bf16 v[40:43], v[112:115], v[182:185], v[40:43]
	v_mfma_f32_16x16x32_bf16 v[36:39], v[108:111], v[182:185], v[36:39]
	v_mfma_f32_16x16x32_bf16 v[32:35], v[104:107], v[182:185], v[32:35]
	v_mfma_f32_16x16x32_bf16 v[28:31], v[156:159], v[178:181], v[28:31]
	v_mfma_f32_16x16x32_bf16 v[24:27], v[112:115], v[178:181], v[24:27]
	v_mfma_f32_16x16x32_bf16 v[20:23], v[108:111], v[178:181], v[20:23]
	v_mfma_f32_16x16x32_bf16 v[16:19], v[104:107], v[178:181], v[16:19]
	v_mfma_f32_16x16x32_bf16 v[12:15], v[156:159], v[166:169], v[12:15]
	v_mfma_f32_16x16x32_bf16 v[8:11], v[112:115], v[166:169], v[8:11]
	v_mfma_f32_16x16x32_bf16 v[4:7], v[108:111], v[166:169], v[4:7]
	v_mfma_f32_16x16x32_bf16 v[0:3], v[104:107], v[166:169], v[0:3]
	s_setprio 0
	ds_read_b128 v[104:107], v124 offset:36864
	ds_read_b128 v[108:111], v124 offset:38912
	ds_read_b128 v[112:115], v124 offset:40960
	ds_read_b128 v[156:159], v124 offset:43008
	ds_read_b128 v[166:169], v124 offset:45056
	ds_read_b128 v[178:181], v125 offset:57344
	ds_read_b128 v[182:185], v125 offset:59392
	ds_read_b128 v[186:189], v125 offset:61440
	ds_read_b128 v[190:193], v125 offset:63488
	s_setprio 1
	s_waitcnt lgkmcnt(3)
	v_mfma_f32_16x16x32_bf16 v[76:79], v[178:181], v[104:107], v[76:79]
	s_waitcnt lgkmcnt(0)
	v_mfma_f32_16x16x32_bf16 v[64:67], v[190:193], v[104:107], v[64:67]
	v_mfma_f32_16x16x32_bf16 v[60:63], v[178:181], v[108:111], v[60:63]
	v_mfma_f32_16x16x32_bf16 v[56:59], v[182:185], v[108:111], v[56:59]
	v_mfma_f32_16x16x32_bf16 v[52:55], v[186:189], v[108:111], v[52:55]
	v_mfma_f32_16x16x32_bf16 v[48:51], v[190:193], v[108:111], v[48:51]
	v_mfma_f32_16x16x32_bf16 v[44:47], v[178:181], v[112:115], v[44:47]
	v_mfma_f32_16x16x32_bf16 v[40:43], v[182:185], v[112:115], v[40:43]
	v_mfma_f32_16x16x32_bf16 v[36:39], v[186:189], v[112:115], v[36:39]
	v_mfma_f32_16x16x32_bf16 v[32:35], v[190:193], v[112:115], v[32:35]
	v_mfma_f32_16x16x32_bf16 v[28:31], v[178:181], v[156:159], v[28:31]
	v_mfma_f32_16x16x32_bf16 v[24:27], v[182:185], v[156:159], v[24:27]
	v_mfma_f32_16x16x32_bf16 v[20:23], v[186:189], v[156:159], v[20:23]
	v_mfma_f32_16x16x32_bf16 v[16:19], v[190:193], v[156:159], v[16:19]
	v_mfma_f32_16x16x32_bf16 v[12:15], v[178:181], v[166:169], v[12:15]
	v_mfma_f32_16x16x32_bf16 v[8:11], v[182:185], v[166:169], v[8:11]
	v_mfma_f32_16x16x32_bf16 v[4:7], v[186:189], v[166:169], v[4:7]
	v_mfma_f32_16x16x32_bf16 v[0:3], v[190:193], v[166:169], v[0:3]
	v_mfma_f32_16x16x32_bf16 v[194:197], v[182:185], v[104:107], v[72:75]
	v_mfma_f32_16x16x32_bf16 v[198:201], v[186:189], v[104:107], v[68:71]
	s_setprio 0
	s_nop 1
	v_mov_b32_e32 v68, v97
	s_waitcnt vmcnt(0)
	s_barrier
	s_movk_i32 s11, 0x50
	s_mov_b32 s10, 0
	s_movk_i32 s11, 0x3200
	s_mov_b64 s[38:39], 0x2000
	s_mov_b64 s[36:37], 0x1000
	v_readfirstlane_b32 s11, v81
	s_mov_b32 m0, s11
	v_readfirstlane_b32 s11, v133
	v_ashrrev_i32_e32 v186, 7, v176
	v_mov_b32_e32 v187, 0x50
	v_and_or_b32 v190, v176, 15, s12
	v_mad_u32_u24 v190, v186, v187, v190
	v_and_b32_e32 v186, 64, v176
	v_lshrrev_b32_e32 v187, 2, v176
	v_and_b32_e32 v187, 12, v187
	v_or3_b32 v191, v186, v187, s13
	v_lshlrev_b32_e32 v204, 12, v190
	v_lshl_add_u32 v204, v191, 2, v204
	v_mov_b32_e32 v115, 0
	v_mov_b32_e32 v114, v204
	v_lshl_add_u64 v[190:191], v[114:115], 0, s[4:5]
	global_load_dwordx4 v[68:71], v[190:191], off
	global_load_dwordx4 v[72:75], v[190:191], off offset:64
	global_load_dwordx4 v[106:109], v[190:191], off offset:128
	global_load_dwordx4 v[110:113], v[190:191], off offset:192
	v_add_u32_e32 v114, 0x10000, v204
	v_lshl_add_u64 v[190:191], v[114:115], 0, s[4:5]
	global_load_dwordx4 v[156:159], v[190:191], off
	global_load_dwordx4 v[166:169], v[190:191], off offset:64
	global_load_dwordx4 v[178:181], v[190:191], off offset:128
	global_load_dwordx4 v[182:185], v[190:191], off offset:192
	v_mov_b32_e32 v114, v204
	v_lshl_add_u64 v[192:193], v[114:115], 0, s[4:5]
	s_waitcnt vmcnt(7)
	v_lshlrev_b32_e32 v186, 16, v212
	v_and_b32_e32 v187, 0xffff0000, v212
	v_pk_fma_f32 v[76:77], v[76:77], v[186:187], v[68:69]
	v_lshlrev_b32_e32 v212, 16, v213
	v_and_b32_e32 v213, 0xffff0000, v213
	v_pk_fma_f32 v[78:79], v[78:79], v[212:213], v[70:71]
	s_nop 0
	global_store_dwordx4 v[192:193], v[76:79], off
	s_waitcnt vmcnt(7)
	v_lshlrev_b32_e32 v186, 16, v214
	v_and_b32_e32 v187, 0xffff0000, v214
	v_pk_fma_f32 v[194:195], v[194:195], v[186:187], v[72:73]
	v_lshlrev_b32_e32 v214, 16, v215
	v_and_b32_e32 v215, 0xffff0000, v215
	v_pk_fma_f32 v[196:197], v[196:197], v[214:215], v[74:75]
	s_nop 0
	global_store_dwordx4 v[192:193], v[194:197], off offset:64
	s_waitcnt vmcnt(7)
	v_lshlrev_b32_e32 v186, 16, v216
	v_and_b32_e32 v187, 0xffff0000, v216
	v_pk_fma_f32 v[198:199], v[198:199], v[186:187], v[106:107]
	v_lshlrev_b32_e32 v216, 16, v217
	v_and_b32_e32 v217, 0xffff0000, v217
	v_pk_fma_f32 v[200:201], v[200:201], v[216:217], v[108:109]
	s_nop 0
	global_store_dwordx4 v[192:193], v[198:201], off offset:128
	s_waitcnt vmcnt(7)
	v_lshlrev_b32_e32 v186, 16, v218
	v_and_b32_e32 v187, 0xffff0000, v218
	v_pk_fma_f32 v[64:65], v[64:65], v[186:187], v[110:111]
	v_lshlrev_b32_e32 v218, 16, v219
	v_and_b32_e32 v219, 0xffff0000, v219
	v_pk_fma_f32 v[66:67], v[66:67], v[218:219], v[112:113]
	s_nop 0
	global_store_dwordx4 v[192:193], v[64:67], off offset:192
	v_add_u32_e32 v114, 0x20000, v204
	v_lshl_add_u64 v[190:191], v[114:115], 0, s[4:5]
	global_load_dwordx4 v[68:71], v[190:191], off
	global_load_dwordx4 v[72:75], v[190:191], off offset:64
	global_load_dwordx4 v[106:109], v[190:191], off offset:128
	global_load_dwordx4 v[110:113], v[190:191], off offset:192
	v_add_u32_e32 v114, 0x10000, v204
	v_lshl_add_u64 v[192:193], v[114:115], 0, s[4:5]
	s_waitcnt vmcnt(11)
	v_lshlrev_b32_e32 v186, 16, v220
	v_and_b32_e32 v187, 0xffff0000, v220
	v_pk_fma_f32 v[60:61], v[60:61], v[186:187], v[156:157]
	v_lshlrev_b32_e32 v220, 16, v221
	v_and_b32_e32 v221, 0xffff0000, v221
	v_pk_fma_f32 v[62:63], v[62:63], v[220:221], v[158:159]
	s_nop 0
	global_store_dwordx4 v[192:193], v[60:63], off
	s_waitcnt vmcnt(11)
	v_lshlrev_b32_e32 v186, 16, v222
	v_and_b32_e32 v187, 0xffff0000, v222
	v_pk_fma_f32 v[56:57], v[56:57], v[186:187], v[166:167]
	v_lshlrev_b32_e32 v222, 16, v223
	v_and_b32_e32 v223, 0xffff0000, v223
	v_pk_fma_f32 v[58:59], v[58:59], v[222:223], v[168:169]
	s_nop 0
	global_store_dwordx4 v[192:193], v[56:59], off offset:64
	s_waitcnt vmcnt(11)
	v_lshlrev_b32_e32 v186, 16, v224
	v_and_b32_e32 v187, 0xffff0000, v224
	v_pk_fma_f32 v[52:53], v[52:53], v[186:187], v[178:179]
	v_lshlrev_b32_e32 v224, 16, v225
	v_and_b32_e32 v225, 0xffff0000, v225
	v_pk_fma_f32 v[54:55], v[54:55], v[224:225], v[180:181]
	s_nop 0
	global_store_dwordx4 v[192:193], v[52:55], off offset:128
	s_waitcnt vmcnt(11)
	v_lshlrev_b32_e32 v186, 16, v226
	v_and_b32_e32 v187, 0xffff0000, v226
	v_pk_fma_f32 v[48:49], v[48:49], v[186:187], v[182:183]
	v_lshlrev_b32_e32 v226, 16, v227
	v_and_b32_e32 v227, 0xffff0000, v227
	v_pk_fma_f32 v[50:51], v[50:51], v[226:227], v[184:185]
	s_nop 0
	global_store_dwordx4 v[192:193], v[48:51], off offset:192
	v_add_u32_e32 v114, 0x30000, v204
	v_lshl_add_u64 v[190:191], v[114:115], 0, s[4:5]
	global_load_dwordx4 v[156:159], v[190:191], off
	global_load_dwordx4 v[166:169], v[190:191], off offset:64
	global_load_dwordx4 v[178:181], v[190:191], off offset:128
	global_load_dwordx4 v[182:185], v[190:191], off offset:192
	v_add_u32_e32 v114, 0x40000, v204
	v_lshl_add_u64 v[190:191], v[114:115], 0, s[4:5]
	global_load_dwordx4 v[212:215], v[190:191], off
	global_load_dwordx4 v[216:219], v[190:191], off offset:64
	global_load_dwordx4 v[220:223], v[190:191], off offset:128
	global_load_dwordx4 v[224:227], v[190:191], off offset:192
	v_add_u32_e32 v114, 0x20000, v204
	v_lshl_add_u64 v[192:193], v[114:115], 0, s[4:5]
	s_waitcnt vmcnt(15)
	v_lshlrev_b32_e32 v186, 16, v202
	v_and_b32_e32 v187, 0xffff0000, v202
	v_pk_fma_f32 v[44:45], v[44:45], v[186:187], v[68:69]
	v_lshlrev_b32_e32 v202, 16, v203
	v_and_b32_e32 v203, 0xffff0000, v203
	v_pk_fma_f32 v[46:47], v[46:47], v[202:203], v[70:71]
	s_nop 0
	global_store_dwordx4 v[192:193], v[44:47], off
	s_waitcnt vmcnt(15)
	v_lshlrev_b32_e32 v186, 16, v210
	v_and_b32_e32 v187, 0xffff0000, v210
	v_pk_fma_f32 v[40:41], v[40:41], v[186:187], v[72:73]
	v_lshlrev_b32_e32 v210, 16, v211
	v_and_b32_e32 v211, 0xffff0000, v211
	v_pk_fma_f32 v[42:43], v[42:43], v[210:211], v[74:75]
	s_nop 0
	global_store_dwordx4 v[192:193], v[40:43], off offset:64
	s_waitcnt vmcnt(15)
	v_lshlrev_b32_e32 v186, 16, v230
	v_and_b32_e32 v187, 0xffff0000, v230
	v_pk_fma_f32 v[36:37], v[36:37], v[186:187], v[106:107]
	v_lshlrev_b32_e32 v230, 16, v231
	v_and_b32_e32 v231, 0xffff0000, v231
	v_pk_fma_f32 v[38:39], v[38:39], v[230:231], v[108:109]
	s_nop 0
	global_store_dwordx4 v[192:193], v[36:39], off offset:128
	s_waitcnt vmcnt(15)
	v_lshlrev_b32_e32 v186, 16, v232
	v_and_b32_e32 v187, 0xffff0000, v232
	v_pk_fma_f32 v[32:33], v[32:33], v[186:187], v[110:111]
	v_lshlrev_b32_e32 v232, 16, v233
	v_and_b32_e32 v233, 0xffff0000, v233
	v_pk_fma_f32 v[34:35], v[34:35], v[232:233], v[112:113]
	s_nop 0
	global_store_dwordx4 v[192:193], v[32:35], off offset:192
	v_add_u32_e32 v114, 0x30000, v204
	v_lshl_add_u64 v[192:193], v[114:115], 0, s[4:5]
	s_waitcnt vmcnt(11)
	v_lshlrev_b32_e32 v186, 16, v234
	v_and_b32_e32 v187, 0xffff0000, v234
	v_pk_fma_f32 v[28:29], v[28:29], v[186:187], v[156:157]
	v_lshlrev_b32_e32 v234, 16, v235
	v_and_b32_e32 v235, 0xffff0000, v235
	v_pk_fma_f32 v[30:31], v[30:31], v[234:235], v[158:159]
	s_nop 0
	global_store_dwordx4 v[192:193], v[28:31], off
	s_waitcnt vmcnt(11)
	v_lshlrev_b32_e32 v186, 16, v236
	v_and_b32_e32 v187, 0xffff0000, v236
	v_pk_fma_f32 v[24:25], v[24:25], v[186:187], v[166:167]
	v_lshlrev_b32_e32 v236, 16, v237
	v_and_b32_e32 v237, 0xffff0000, v237
	v_pk_fma_f32 v[26:27], v[26:27], v[236:237], v[168:169]
	s_nop 0
	global_store_dwordx4 v[192:193], v[24:27], off offset:64
	s_waitcnt vmcnt(11)
	v_lshlrev_b32_e32 v186, 16, v238
	v_and_b32_e32 v187, 0xffff0000, v238
	v_pk_fma_f32 v[20:21], v[20:21], v[186:187], v[178:179]
	v_lshlrev_b32_e32 v238, 16, v239
	v_and_b32_e32 v239, 0xffff0000, v239
	v_pk_fma_f32 v[22:23], v[22:23], v[238:239], v[180:181]
	s_nop 0
	global_store_dwordx4 v[192:193], v[20:23], off offset:128
	s_waitcnt vmcnt(11)
	v_lshlrev_b32_e32 v186, 16, v240
	v_and_b32_e32 v187, 0xffff0000, v240
	v_pk_fma_f32 v[16:17], v[16:17], v[186:187], v[182:183]
	v_lshlrev_b32_e32 v240, 16, v241
	v_and_b32_e32 v241, 0xffff0000, v241
	v_pk_fma_f32 v[18:19], v[18:19], v[240:241], v[184:185]
	s_nop 0
	global_store_dwordx4 v[192:193], v[16:19], off offset:192
	v_add_u32_e32 v114, 0x40000, v204
	v_lshl_add_u64 v[192:193], v[114:115], 0, s[4:5]
	s_waitcnt vmcnt(11)
	v_lshlrev_b32_e32 v186, 16, v242
	v_and_b32_e32 v187, 0xffff0000, v242
	v_pk_fma_f32 v[12:13], v[12:13], v[186:187], v[212:213]
	v_lshlrev_b32_e32 v242, 16, v243
	v_and_b32_e32 v243, 0xffff0000, v243
	v_pk_fma_f32 v[14:15], v[14:15], v[242:243], v[214:215]
	s_nop 0
	global_store_dwordx4 v[192:193], v[12:15], off
	s_waitcnt vmcnt(11)
	v_lshlrev_b32_e32 v186, 16, v244
	v_and_b32_e32 v187, 0xffff0000, v244
	v_pk_fma_f32 v[8:9], v[8:9], v[186:187], v[216:217]
	v_lshlrev_b32_e32 v244, 16, v245
	v_and_b32_e32 v245, 0xffff0000, v245
	v_pk_fma_f32 v[10:11], v[10:11], v[244:245], v[218:219]
	s_nop 0
	global_store_dwordx4 v[192:193], v[8:11], off offset:64
	s_waitcnt vmcnt(11)
	v_lshlrev_b32_e32 v186, 16, v246
	v_and_b32_e32 v187, 0xffff0000, v246
	v_pk_fma_f32 v[4:5], v[4:5], v[186:187], v[220:221]
	v_lshlrev_b32_e32 v246, 16, v247
	v_and_b32_e32 v247, 0xffff0000, v247
	v_pk_fma_f32 v[6:7], v[6:7], v[246:247], v[222:223]
	s_nop 0
	global_store_dwordx4 v[192:193], v[4:7], off offset:128
	s_waitcnt vmcnt(11)
	v_lshlrev_b32_e32 v186, 16, v248
	v_and_b32_e32 v187, 0xffff0000, v248
	v_pk_fma_f32 v[0:1], v[0:1], v[186:187], v[224:225]
	v_lshlrev_b32_e32 v248, 16, v249
	v_and_b32_e32 v249, 0xffff0000, v249
	v_pk_fma_f32 v[2:3], v[2:3], v[248:249], v[226:227]
	s_nop 0
	global_store_dwordx4 v[192:193], v[0:3], off offset:192
	s_nop 1
	v_lshl_add_u64 v[0:1], v[102:103], 0, v[96:97]
	v_lshl_add_u64 v[2:3], v[0:1], 0, s[36:37]
	s_mov_b64 s[36:37], 0x65000
	global_load_lds_dwordx4 v[2:3], off
	v_lshl_add_u64 v[2:3], v[0:1], 0, s[36:37]
	s_mov_b32 m0, s11
	s_mov_b64 s[36:37], 0xc9000
	v_readfirstlane_b32 s11, v132
	global_load_lds_dwordx4 v[2:3], off
	v_lshl_add_u64 v[2:3], v[0:1], 0, s[36:37]
	s_mov_b32 m0, s11
	s_mov_b64 s[36:37], 0x12d000
	v_readfirstlane_b32 s11, v131
	global_load_lds_dwordx4 v[2:3], off
	v_lshl_add_u64 v[2:3], v[0:1], 0, s[36:37]
	s_mov_b32 m0, s11
	s_mov_b64 s[36:37], 0x191000
	v_readfirstlane_b32 s11, v130
	global_load_lds_dwordx4 v[2:3], off
	v_lshl_add_u64 v[0:1], v[0:1], 0, s[36:37]
	s_mov_b32 m0, s11
	s_nop 0
	global_load_lds_dwordx4 v[0:1], off
	v_lshl_add_u64 v[0:1], v[88:89], 0, s[8:9]
	v_readfirstlane_b32 s8, v129
	s_mov_b32 m0, s8
	v_readfirstlane_b32 s8, v128
	global_load_lds_dwordx4 v[0:1], off
	v_lshl_add_u64 v[2:3], v[0:1], 0, s[40:41]
	s_mov_b32 m0, s8
	s_mov_b64 s[8:9], 0x20000
	global_load_lds_dwordx4 v[2:3], off
	v_lshl_add_u64 v[2:3], v[0:1], 0, s[8:9]
	v_readfirstlane_b32 s8, v127
	s_mov_b32 m0, s8
	s_mov_b64 s[8:9], 0x30000
	v_lshl_add_u64 v[0:1], v[0:1], 0, s[8:9]
	v_readfirstlane_b32 s8, v126
	global_load_lds_dwordx4 v[2:3], off
	s_mov_b32 m0, s8
	s_mov_b64 s[8:9], 0
	global_load_lds_dwordx4 v[0:1], off
	s_waitcnt vmcnt(0)
	v_mov_b32_e32 v0, 0
	v_mov_b32_e32 v1, v0
	v_mov_b32_e32 v2, v0
	v_mov_b32_e32 v3, v0
	v_mov_b32_e32 v4, v0
	v_mov_b32_e32 v5, v0
	v_mov_b32_e32 v6, v0
	v_mov_b32_e32 v7, v0
	v_mov_b32_e32 v8, v0
	v_mov_b32_e32 v9, v0
	v_mov_b32_e32 v10, v0
	v_mov_b32_e32 v11, v0
	v_mov_b32_e32 v12, v0
	v_mov_b32_e32 v13, v0
	v_mov_b32_e32 v14, v0
	v_mov_b32_e32 v15, v0
	v_mov_b32_e32 v16, v0
	v_mov_b32_e32 v17, v0
	v_mov_b32_e32 v18, v0
	v_mov_b32_e32 v19, v0
	v_mov_b32_e32 v20, v0
	v_mov_b32_e32 v21, v0
	v_mov_b32_e32 v22, v0
	v_mov_b32_e32 v23, v0
	v_mov_b32_e32 v24, v0
	v_mov_b32_e32 v25, v0
	v_mov_b32_e32 v26, v0
	v_mov_b32_e32 v27, v0
	v_mov_b32_e32 v28, v0
	v_mov_b32_e32 v29, v0
	v_mov_b32_e32 v30, v0
	v_mov_b32_e32 v31, v0
	v_mov_b32_e32 v32, v0
	v_mov_b32_e32 v33, v0
	v_mov_b32_e32 v34, v0
	v_mov_b32_e32 v35, v0
	v_mov_b32_e32 v36, v0
	v_mov_b32_e32 v37, v0
	v_mov_b32_e32 v38, v0
	v_mov_b32_e32 v39, v0
	v_mov_b32_e32 v40, v0
	v_mov_b32_e32 v41, v0
	v_mov_b32_e32 v42, v0
	v_mov_b32_e32 v43, v0
	v_mov_b32_e32 v44, v0
	v_mov_b32_e32 v45, v0
	v_mov_b32_e32 v46, v0
	v_mov_b32_e32 v47, v0
	v_mov_b32_e32 v48, v0
	v_mov_b32_e32 v49, v0
	v_mov_b32_e32 v50, v0
	v_mov_b32_e32 v51, v0
	v_mov_b32_e32 v52, v0
	v_mov_b32_e32 v53, v0
	v_mov_b32_e32 v54, v0
	v_mov_b32_e32 v55, v0
	v_mov_b32_e32 v56, v0
	v_mov_b32_e32 v57, v0
	v_mov_b32_e32 v58, v0
	v_mov_b32_e32 v59, v0
	v_mov_b32_e32 v60, v0
	v_mov_b32_e32 v61, v0
	v_mov_b32_e32 v62, v0
	v_mov_b32_e32 v63, v0
	v_mov_b32_e32 v64, v0
	v_mov_b32_e32 v65, v0
	v_mov_b32_e32 v66, v0
	v_mov_b32_e32 v67, v0
	v_mov_b32_e32 v68, v0
	v_mov_b32_e32 v69, v0
	v_mov_b32_e32 v70, v0
	v_mov_b32_e32 v71, v0
	v_mov_b32_e32 v72, v0
	v_mov_b32_e32 v73, v0
	v_mov_b32_e32 v74, v0
	v_mov_b32_e32 v75, v0
	v_mov_b32_e32 v76, v0
	v_mov_b32_e32 v77, v0
	v_mov_b32_e32 v78, v0
	v_mov_b32_e32 v79, v0
	s_waitcnt vmcnt(0) lgkmcnt(0)
	s_barrier
.LBB0_90:
	s_add_i32 s11, s10, 1
	s_bitcmp1_b32 s11, 0
	s_cselect_b32 s35, 0x9000, 0
	v_add_u32_e32 v96, s35, v81
	v_lshl_add_u64 v[102:103], v[94:95], 0, s[8:9]
	s_mov_b64 s[36:37], 0x6182080
	v_readfirstlane_b32 s35, v96
	v_add_u32_e32 v106, 0x1000, v96
	v_lshl_add_u64 v[104:105], v[102:103], 0, s[36:37]
	s_mov_b32 m0, s35
	s_mov_b64 s[36:37], 0x61e6080
	v_readfirstlane_b32 s35, v106
	v_add_u32_e32 v106, 0x2000, v96
	global_load_lds_dwordx4 v[104:105], off
	v_lshl_add_u64 v[104:105], v[102:103], 0, s[36:37]
	s_mov_b32 m0, s35
	s_mov_b64 s[36:37], 0x624a080
	v_readfirstlane_b32 s35, v106
	v_add_u32_e32 v106, 0x3000, v96
	global_load_lds_dwordx4 v[104:105], off
	v_lshl_add_u64 v[104:105], v[102:103], 0, s[36:37]
	s_mov_b32 m0, s35
	s_mov_b64 s[36:37], 0x62ae080
	v_readfirstlane_b32 s35, v106
	global_load_lds_dwordx4 v[104:105], off
	v_lshl_add_u64 v[104:105], v[102:103], 0, s[36:37]
	s_mov_b32 m0, s35
	s_mov_b64 s[36:37], 0x6312080
	global_load_lds_dwordx4 v[104:105], off
	v_add_u32_e32 v104, 0x4000, v96
	v_lshl_add_u64 v[102:103], v[102:103], 0, s[36:37]
	v_readfirstlane_b32 s35, v104
	s_mov_b32 m0, s35
	v_add_u32_e32 v106, 0x5000, v96
	global_load_lds_dwordx4 v[102:103], off
	v_lshl_add_u64 v[102:103], v[100:101], 0, s[8:9]
	s_mov_b64 s[36:37], 0x14931080
	v_readfirstlane_b32 s35, v106
	v_add_u32_e32 v106, 0x6000, v96
	v_lshl_add_u64 v[104:105], v[102:103], 0, s[36:37]
	s_mov_b32 m0, s35
	s_mov_b64 s[36:37], 0x14941080
	v_readfirstlane_b32 s35, v106
	v_add_u32_e32 v106, 0x7000, v96
	global_load_lds_dwordx4 v[104:105], off
	v_lshl_add_u64 v[104:105], v[102:103], 0, s[36:37]
	s_mov_b32 m0, s35
	s_mov_b64 s[36:37], 0x14951080
	v_readfirstlane_b32 s35, v106
	v_add_u32_e32 v96, 0x8000, v96
	global_load_lds_dwordx4 v[104:105], off
	v_lshl_add_u64 v[104:105], v[102:103], 0, s[36:37]
	s_mov_b32 m0, s35
	s_mov_b64 s[36:37], 0x14961080
	v_readfirstlane_b32 s35, v96
	global_load_lds_dwordx4 v[104:105], off
	v_lshl_add_u64 v[102:103], v[102:103], 0, s[36:37]
	s_mov_b32 m0, s35
	s_bitcmp1_b32 s10, 0
	global_load_lds_dwordx4 v[102:103], off
	s_cselect_b32 s10, 0x9000, 0
	s_add_i32 s10, s10, 0
	v_add_u32_e32 v96, s10, v116
	v_add_u32_e32 v114, v96, v117
	ds_read_b128 v[102:105], v114
	ds_read_b128 v[106:109], v114 offset:2048
	ds_read_b128 v[110:113], v114 offset:4096
	ds_read_b128 v[126:129], v114 offset:6144
	v_add_u32_e32 v96, v96, v118
	ds_read_b128 v[130:133], v114 offset:8192
	ds_read_b128 v[156:159], v96 offset:20480
	ds_read_b128 v[166:169], v96 offset:22528
	ds_read_b128 v[178:181], v96 offset:24576
	ds_read_b128 v[182:185], v96 offset:26624
	v_add_u32_e32 v210, s10, v119
	v_add_u32_e32 v211, v210, v117
	ds_read_b128 v[212:215], v211
	ds_read_b128 v[216:219], v211 offset:2048
	ds_read_b128 v[220:223], v211 offset:4096
	ds_read_b128 v[224:227], v211 offset:6144
	v_add_u32_e32 v228, v210, v118
	ds_read_b128 v[230:233], v211 offset:8192
	ds_read_b128 v[234:237], v228 offset:20480
	ds_read_b128 v[238:241], v228 offset:22528
	ds_read_b128 v[242:245], v228 offset:24576
	ds_read_b128 v[246:249], v228 offset:26624
	s_setprio 1
	s_waitcnt lgkmcnt(9)
	v_mfma_f32_16x16x32_bf16 v[76:79], v[156:159], v[102:105], v[76:79]
	v_mfma_f32_16x16x32_bf16 v[72:75], v[166:169], v[102:105], v[72:75]
	v_mfma_f32_16x16x32_bf16 v[68:71], v[178:181], v[102:105], v[68:71]
	v_mfma_f32_16x16x32_bf16 v[64:67], v[182:185], v[102:105], v[64:67]
	v_mfma_f32_16x16x32_bf16 v[60:63], v[156:159], v[106:109], v[60:63]
	v_mfma_f32_16x16x32_bf16 v[56:59], v[166:169], v[106:109], v[56:59]
	v_mfma_f32_16x16x32_bf16 v[52:55], v[178:181], v[106:109], v[52:55]
	v_mfma_f32_16x16x32_bf16 v[48:51], v[182:185], v[106:109], v[48:51]
	v_mfma_f32_16x16x32_bf16 v[44:47], v[156:159], v[110:113], v[44:47]
	v_mfma_f32_16x16x32_bf16 v[40:43], v[166:169], v[110:113], v[40:43]
	v_mfma_f32_16x16x32_bf16 v[36:39], v[178:181], v[110:113], v[36:39]
	v_mfma_f32_16x16x32_bf16 v[32:35], v[182:185], v[110:113], v[32:35]
	v_mfma_f32_16x16x32_bf16 v[28:31], v[156:159], v[126:129], v[28:31]
	v_mfma_f32_16x16x32_bf16 v[24:27], v[166:169], v[126:129], v[24:27]
	v_mfma_f32_16x16x32_bf16 v[20:23], v[178:181], v[126:129], v[20:23]
	v_mfma_f32_16x16x32_bf16 v[16:19], v[182:185], v[126:129], v[16:19]
	v_mfma_f32_16x16x32_bf16 v[12:15], v[156:159], v[130:133], v[12:15]
	v_mfma_f32_16x16x32_bf16 v[8:11], v[166:169], v[130:133], v[8:11]
	v_mfma_f32_16x16x32_bf16 v[4:7], v[178:181], v[130:133], v[4:7]
	v_mfma_f32_16x16x32_bf16 v[0:3], v[182:185], v[130:133], v[0:3]
	s_setprio 0
	s_setprio 1
	s_waitcnt lgkmcnt(0)
	v_mfma_f32_16x16x32_bf16 v[76:79], v[234:237], v[212:215], v[76:79]
	v_mfma_f32_16x16x32_bf16 v[72:75], v[238:241], v[212:215], v[72:75]
	v_mfma_f32_16x16x32_bf16 v[68:71], v[242:245], v[212:215], v[68:71]
	v_mfma_f32_16x16x32_bf16 v[64:67], v[246:249], v[212:215], v[64:67]
	v_mfma_f32_16x16x32_bf16 v[60:63], v[234:237], v[216:219], v[60:63]
	v_mfma_f32_16x16x32_bf16 v[56:59], v[238:241], v[216:219], v[56:59]
	v_mfma_f32_16x16x32_bf16 v[52:55], v[242:245], v[216:219], v[52:55]
	v_mfma_f32_16x16x32_bf16 v[48:51], v[246:249], v[216:219], v[48:51]
	v_mfma_f32_16x16x32_bf16 v[44:47], v[234:237], v[220:223], v[44:47]
	v_mfma_f32_16x16x32_bf16 v[40:43], v[238:241], v[220:223], v[40:43]
	v_mfma_f32_16x16x32_bf16 v[36:39], v[242:245], v[220:223], v[36:39]
	v_mfma_f32_16x16x32_bf16 v[32:35], v[246:249], v[220:223], v[32:35]
	v_mfma_f32_16x16x32_bf16 v[28:31], v[234:237], v[224:227], v[28:31]
	v_mfma_f32_16x16x32_bf16 v[24:27], v[238:241], v[224:227], v[24:27]
	v_mfma_f32_16x16x32_bf16 v[20:23], v[242:245], v[224:227], v[20:23]
	v_mfma_f32_16x16x32_bf16 v[16:19], v[246:249], v[224:227], v[16:19]
	v_mfma_f32_16x16x32_bf16 v[12:15], v[234:237], v[230:233], v[12:15]
	v_mfma_f32_16x16x32_bf16 v[8:11], v[238:241], v[230:233], v[8:11]
	v_mfma_f32_16x16x32_bf16 v[4:7], v[242:245], v[230:233], v[4:7]
	v_mfma_f32_16x16x32_bf16 v[0:3], v[246:249], v[230:233], v[0:3]
	s_setprio 0
	s_waitcnt vmcnt(0)
	s_add_u32 s8, s8, 0x80
	s_addc_u32 s9, s9, 0
	s_cmpk_lg_i32 s8, 0x780
	s_mov_b32 s10, s11
	s_waitcnt vmcnt(0)
	s_barrier
	s_cbranch_scc1 .LBB0_90
	v_ashrrev_i32_e32 v242, 7, v176
	v_mov_b32_e32 v243, 0x50
	v_and_or_b32 v248, v176, 15, s12
	v_mad_u32_u24 v248, v242, v243, v248
	v_and_b32_e32 v242, 64, v176
	v_lshrrev_b32_e32 v243, 2, v176
	v_and_b32_e32 v243, 12, v243
	v_or3_b32 v249, v242, v243, s13
	v_mul_u32_u24_e32 v244, 0x3200, v248
	v_lshl_add_u32 v244, v249, 1, v244
	v_add_u32_e32 v244, 0x2800, v244
	v_mov_b32_e32 v247, 0
	v_mov_b32_e32 v246, v244
	v_lshl_add_u64 v[248:249], v[246:247], 0, s[0:1]
	global_load_dwordx2 v[212:213], v[248:249], off
	global_load_dwordx2 v[214:215], v[248:249], off offset:32
	global_load_dwordx2 v[216:217], v[248:249], off offset:64
	global_load_dwordx2 v[218:219], v[248:249], off offset:96
	v_add_u32_e32 v246, 0x32000, v244
	v_lshl_add_u64 v[248:249], v[246:247], 0, s[0:1]
	global_load_dwordx2 v[220:221], v[248:249], off
	global_load_dwordx2 v[222:223], v[248:249], off offset:32
	global_load_dwordx2 v[224:225], v[248:249], off offset:64
	global_load_dwordx2 v[226:227], v[248:249], off offset:96
	v_add_u32_e32 v246, 0x64000, v244
	v_lshl_add_u64 v[248:249], v[246:247], 0, s[0:1]
	global_load_dwordx2 v[202:203], v[248:249], off
	global_load_dwordx2 v[210:211], v[248:249], off offset:32
	global_load_dwordx2 v[230:231], v[248:249], off offset:64
	global_load_dwordx2 v[232:233], v[248:249], off offset:96
	v_add_u32_e32 v246, 0x96000, v244
	v_lshl_add_u64 v[248:249], v[246:247], 0, s[0:1]
	global_load_dwordx2 v[234:235], v[248:249], off
	global_load_dwordx2 v[236:237], v[248:249], off offset:32
	global_load_dwordx2 v[238:239], v[248:249], off offset:64
	global_load_dwordx2 v[240:241], v[248:249], off offset:96
	v_add_u32_e32 v246, 0xc8000, v244
	v_lshl_add_u64 v[248:249], v[246:247], 0, s[0:1]
	global_load_dwordx2 v[242:243], v[248:249], off
	global_load_dwordx2 v[244:245], v[248:249], off offset:32
	global_load_dwordx2 v[246:247], v[248:249], off offset:64
	global_load_dwordx2 v[248:249], v[248:249], off offset:96
	ds_read_b128 v[100:103], v122 offset:63488
	ds_read_b128 v[104:107], v122 offset:61440
	ds_read_b128 v[108:111], v122 offset:59392
	ds_read_b128 v[112:115], v122 offset:57344
	ds_read_b128 v[126:129], v123 offset:45056
	ds_read_b128 v[130:133], v123 offset:43008
	ds_read_b128 v[156:159], v123 offset:40960
	ds_read_b128 v[166:169], v123 offset:38912
	ds_read_b128 v[178:181], v123 offset:36864
	s_setprio 1
	s_waitcnt lgkmcnt(0)
	v_mfma_f32_16x16x32_bf16 v[76:79], v[112:115], v[178:181], v[76:79]
	v_mfma_f32_16x16x32_bf16 v[72:75], v[108:111], v[178:181], v[72:75]
	v_mfma_f32_16x16x32_bf16 v[68:71], v[104:107], v[178:181], v[68:71]
	v_mfma_f32_16x16x32_bf16 v[64:67], v[100:103], v[178:181], v[64:67]
	v_mfma_f32_16x16x32_bf16 v[60:63], v[112:115], v[166:169], v[60:63]
	v_mfma_f32_16x16x32_bf16 v[56:59], v[108:111], v[166:169], v[56:59]
	v_mfma_f32_16x16x32_bf16 v[52:55], v[104:107], v[166:169], v[52:55]
	v_mfma_f32_16x16x32_bf16 v[48:51], v[100:103], v[166:169], v[48:51]
	v_mfma_f32_16x16x32_bf16 v[44:47], v[112:115], v[156:159], v[44:47]
	v_mfma_f32_16x16x32_bf16 v[40:43], v[108:111], v[156:159], v[40:43]
	v_mfma_f32_16x16x32_bf16 v[36:39], v[104:107], v[156:159], v[36:39]
	v_mfma_f32_16x16x32_bf16 v[32:35], v[100:103], v[156:159], v[32:35]
	v_mfma_f32_16x16x32_bf16 v[28:31], v[112:115], v[130:133], v[28:31]
	v_mfma_f32_16x16x32_bf16 v[24:27], v[108:111], v[130:133], v[24:27]
	v_mfma_f32_16x16x32_bf16 v[20:23], v[104:107], v[130:133], v[20:23]
	v_mfma_f32_16x16x32_bf16 v[16:19], v[100:103], v[130:133], v[16:19]
	v_mfma_f32_16x16x32_bf16 v[12:15], v[112:115], v[126:129], v[12:15]
	v_mfma_f32_16x16x32_bf16 v[8:11], v[108:111], v[126:129], v[8:11]
	v_mfma_f32_16x16x32_bf16 v[4:7], v[104:107], v[126:129], v[4:7]
	v_mfma_f32_16x16x32_bf16 v[0:3], v[100:103], v[126:129], v[0:3]
	s_setprio 0
	ds_read_b128 v[100:103], v124 offset:36864
	ds_read_b128 v[104:107], v124 offset:38912
	ds_read_b128 v[108:111], v124 offset:40960
	ds_read_b128 v[112:115], v124 offset:43008
	ds_read_b128 v[126:129], v124 offset:45056
	ds_read_b128 v[130:133], v125 offset:57344
	ds_read_b128 v[156:159], v125 offset:59392
	ds_read_b128 v[166:169], v125 offset:61440
	ds_read_b128 v[122:125], v125 offset:63488
	s_setprio 1
	s_waitcnt lgkmcnt(3)
	v_mfma_f32_16x16x32_bf16 v[178:181], v[130:133], v[100:103], v[76:79]
	s_waitcnt lgkmcnt(2)
	v_mfma_f32_16x16x32_bf16 v[72:75], v[156:159], v[100:103], v[72:75]
	s_waitcnt lgkmcnt(1)
	v_mfma_f32_16x16x32_bf16 v[68:71], v[166:169], v[100:103], v[68:71]
	s_waitcnt lgkmcnt(0)
	v_mfma_f32_16x16x32_bf16 v[64:67], v[122:125], v[100:103], v[64:67]
	v_mfma_f32_16x16x32_bf16 v[60:63], v[130:133], v[104:107], v[60:63]
	v_mfma_f32_16x16x32_bf16 v[56:59], v[156:159], v[104:107], v[56:59]
	v_mfma_f32_16x16x32_bf16 v[52:55], v[166:169], v[104:107], v[52:55]
	v_mfma_f32_16x16x32_bf16 v[48:51], v[122:125], v[104:107], v[48:51]
	v_mfma_f32_16x16x32_bf16 v[44:47], v[130:133], v[108:111], v[44:47]
	v_mfma_f32_16x16x32_bf16 v[40:43], v[156:159], v[108:111], v[40:43]
	v_mfma_f32_16x16x32_bf16 v[36:39], v[166:169], v[108:111], v[36:39]
	v_mfma_f32_16x16x32_bf16 v[32:35], v[122:125], v[108:111], v[32:35]
	v_mfma_f32_16x16x32_bf16 v[28:31], v[130:133], v[112:115], v[28:31]
	v_mfma_f32_16x16x32_bf16 v[24:27], v[156:159], v[112:115], v[24:27]
	v_mfma_f32_16x16x32_bf16 v[20:23], v[166:169], v[112:115], v[20:23]
	v_mfma_f32_16x16x32_bf16 v[16:19], v[122:125], v[112:115], v[16:19]
	v_mfma_f32_16x16x32_bf16 v[12:15], v[130:133], v[126:129], v[12:15]
	v_mfma_f32_16x16x32_bf16 v[8:11], v[156:159], v[126:129], v[8:11]
	v_mfma_f32_16x16x32_bf16 v[4:7], v[166:169], v[126:129], v[4:7]
	v_mfma_f32_16x16x32_bf16 v[0:3], v[122:125], v[126:129], v[0:3]
	s_setprio 0
	v_mov_b32_e32 v76, v97
	s_waitcnt vmcnt(0)
	s_barrier
	v_ashrrev_i32_e32 v198, 7, v176
	v_mov_b32_e32 v199, 0x50
	v_and_or_b32 v206, v176, 15, s12
	v_mad_u32_u24 v206, v198, v199, v206
	v_and_b32_e32 v198, 64, v176
	v_lshrrev_b32_e32 v199, 2, v176
	v_and_b32_e32 v199, 12, v199
	v_or3_b32 v207, v198, v199, s13
	v_lshlrev_b32_e32 v194, 12, v206
	v_lshl_add_u32 v194, v207, 2, v194
	v_lshlrev_b32_e32 v195, 11, v206
	v_lshl_add_u32 v195, v207, 1, v195
	v_mov_b32_e32 v115, 0
	v_mov_b32_e32 v114, v194
	v_lshl_add_u64 v[206:207], v[114:115], 0, s[4:5]
	global_load_dwordx4 v[76:79], v[206:207], off
	global_load_dwordx4 v[106:109], v[206:207], off offset:64
	global_load_dwordx4 v[110:113], v[206:207], off offset:128
	global_load_dwordx4 v[122:125], v[206:207], off offset:192
	v_add_u32_e32 v114, 0x10000, v194
	v_lshl_add_u64 v[206:207], v[114:115], 0, s[4:5]
	global_load_dwordx4 v[126:129], v[206:207], off
	global_load_dwordx4 v[130:133], v[206:207], off offset:64
	global_load_dwordx4 v[156:159], v[206:207], off offset:128
	global_load_dwordx4 v[166:169], v[206:207], off offset:192
	v_mov_b32_e32 v114, v195
	v_lshl_add_u64 v[200:201], v[114:115], 0, s[6:7]
	s_waitcnt vmcnt(7)
	v_lshlrev_b32_e32 v198, 16, v212
	v_and_b32_e32 v199, 0xffff0000, v212
	v_pk_fma_f32 v[178:179], v[178:179], v[198:199], v[76:77]
	v_lshlrev_b32_e32 v212, 16, v213
	v_and_b32_e32 v213, 0xffff0000, v213
	v_pk_fma_f32 v[180:181], v[180:181], v[212:213], v[78:79]
	s_nop 0
	v_bfe_u32 v198, v178, 16, 1
	v_add3_u32 v178, v178, v198, s33
	v_bfe_u32 v198, v179, 16, 1
	v_add3_u32 v179, v179, v198, s33
	v_bfe_u32 v198, v180, 16, 1
	v_add3_u32 v180, v180, v198, s33
	v_bfe_u32 v198, v181, 16, 1
	v_add3_u32 v181, v181, v198, s33
	v_perm_b32 v178, v179, v178, s96
	v_perm_b32 v179, v181, v180, s96
	global_store_dwordx2 v[200:201], v[178:179], off
	s_waitcnt vmcnt(7)
	v_lshlrev_b32_e32 v198, 16, v214
	v_and_b32_e32 v199, 0xffff0000, v214
	v_pk_fma_f32 v[72:73], v[72:73], v[198:199], v[106:107]
	v_lshlrev_b32_e32 v214, 16, v215
	v_and_b32_e32 v215, 0xffff0000, v215
	v_pk_fma_f32 v[74:75], v[74:75], v[214:215], v[108:109]
	s_nop 0
	v_bfe_u32 v198, v72, 16, 1
	v_add3_u32 v72, v72, v198, s33
	v_bfe_u32 v198, v73, 16, 1
	v_add3_u32 v73, v73, v198, s33
	v_bfe_u32 v198, v74, 16, 1
	v_add3_u32 v74, v74, v198, s33
	v_bfe_u32 v198, v75, 16, 1
	v_add3_u32 v75, v75, v198, s33
	v_perm_b32 v72, v73, v72, s96
	v_perm_b32 v73, v75, v74, s96
	global_store_dwordx2 v[200:201], v[72:73], off offset:32
	s_waitcnt vmcnt(7)
	v_lshlrev_b32_e32 v198, 16, v216
	v_and_b32_e32 v199, 0xffff0000, v216
	v_pk_fma_f32 v[68:69], v[68:69], v[198:199], v[110:111]
	v_lshlrev_b32_e32 v216, 16, v217
	v_and_b32_e32 v217, 0xffff0000, v217
	v_pk_fma_f32 v[70:71], v[70:71], v[216:217], v[112:113]
	s_nop 0
	v_bfe_u32 v198, v68, 16, 1
	v_add3_u32 v68, v68, v198, s33
	v_bfe_u32 v198, v69, 16, 1
	v_add3_u32 v69, v69, v198, s33
	v_bfe_u32 v198, v70, 16, 1
	v_add3_u32 v70, v70, v198, s33
	v_bfe_u32 v198, v71, 16, 1
	v_add3_u32 v71, v71, v198, s33
	v_perm_b32 v68, v69, v68, s96
	v_perm_b32 v69, v71, v70, s96
	global_store_dwordx2 v[200:201], v[68:69], off offset:64
	s_waitcnt vmcnt(7)
	v_lshlrev_b32_e32 v198, 16, v218
	v_and_b32_e32 v199, 0xffff0000, v218
	v_pk_fma_f32 v[64:65], v[64:65], v[198:199], v[122:123]
	v_lshlrev_b32_e32 v218, 16, v219
	v_and_b32_e32 v219, 0xffff0000, v219
	v_pk_fma_f32 v[66:67], v[66:67], v[218:219], v[124:125]
	s_nop 0
	v_bfe_u32 v198, v64, 16, 1
	v_add3_u32 v64, v64, v198, s33
	v_bfe_u32 v198, v65, 16, 1
	v_add3_u32 v65, v65, v198, s33
	v_bfe_u32 v198, v66, 16, 1
	v_add3_u32 v66, v66, v198, s33
	v_bfe_u32 v198, v67, 16, 1
	v_add3_u32 v67, v67, v198, s33
	v_perm_b32 v64, v65, v64, s96
	v_perm_b32 v65, v67, v66, s96
	global_store_dwordx2 v[200:201], v[64:65], off offset:96
	v_add_u32_e32 v114, 0x20000, v194
	v_lshl_add_u64 v[206:207], v[114:115], 0, s[4:5]
	global_load_dwordx4 v[76:79], v[206:207], off
	global_load_dwordx4 v[106:109], v[206:207], off offset:64
	global_load_dwordx4 v[110:113], v[206:207], off offset:128
	global_load_dwordx4 v[122:125], v[206:207], off offset:192
	v_add_u32_e32 v114, 0x8000, v195
	v_lshl_add_u64 v[200:201], v[114:115], 0, s[6:7]
	s_waitcnt vmcnt(11)
	v_lshlrev_b32_e32 v198, 16, v220
	v_and_b32_e32 v199, 0xffff0000, v220
	v_pk_fma_f32 v[60:61], v[60:61], v[198:199], v[126:127]
	v_lshlrev_b32_e32 v220, 16, v221
	v_and_b32_e32 v221, 0xffff0000, v221
	v_pk_fma_f32 v[62:63], v[62:63], v[220:221], v[128:129]
	s_nop 0
	v_bfe_u32 v198, v60, 16, 1
	v_add3_u32 v60, v60, v198, s33
	v_bfe_u32 v198, v61, 16, 1
	v_add3_u32 v61, v61, v198, s33
	v_bfe_u32 v198, v62, 16, 1
	v_add3_u32 v62, v62, v198, s33
	v_bfe_u32 v198, v63, 16, 1
	v_add3_u32 v63, v63, v198, s33
	v_perm_b32 v60, v61, v60, s96
	v_perm_b32 v61, v63, v62, s96
	global_store_dwordx2 v[200:201], v[60:61], off
	s_waitcnt vmcnt(11)
	v_lshlrev_b32_e32 v198, 16, v222
	v_and_b32_e32 v199, 0xffff0000, v222
	v_pk_fma_f32 v[56:57], v[56:57], v[198:199], v[130:131]
	v_lshlrev_b32_e32 v222, 16, v223
	v_and_b32_e32 v223, 0xffff0000, v223
	v_pk_fma_f32 v[58:59], v[58:59], v[222:223], v[132:133]
	s_nop 0
	v_bfe_u32 v198, v56, 16, 1
	v_add3_u32 v56, v56, v198, s33
	v_bfe_u32 v198, v57, 16, 1
	v_add3_u32 v57, v57, v198, s33
	v_bfe_u32 v198, v58, 16, 1
	v_add3_u32 v58, v58, v198, s33
	v_bfe_u32 v198, v59, 16, 1
	v_add3_u32 v59, v59, v198, s33
	v_perm_b32 v56, v57, v56, s96
	v_perm_b32 v57, v59, v58, s96
	global_store_dwordx2 v[200:201], v[56:57], off offset:32
	s_waitcnt vmcnt(11)
	v_lshlrev_b32_e32 v198, 16, v224
	v_and_b32_e32 v199, 0xffff0000, v224
	v_pk_fma_f32 v[52:53], v[52:53], v[198:199], v[156:157]
	v_lshlrev_b32_e32 v224, 16, v225
	v_and_b32_e32 v225, 0xffff0000, v225
	v_pk_fma_f32 v[54:55], v[54:55], v[224:225], v[158:159]
	s_nop 0
	v_bfe_u32 v198, v52, 16, 1
	v_add3_u32 v52, v52, v198, s33
	v_bfe_u32 v198, v53, 16, 1
	v_add3_u32 v53, v53, v198, s33
	v_bfe_u32 v198, v54, 16, 1
	v_add3_u32 v54, v54, v198, s33
	v_bfe_u32 v198, v55, 16, 1
	v_add3_u32 v55, v55, v198, s33
	v_perm_b32 v52, v53, v52, s96
	v_perm_b32 v53, v55, v54, s96
	global_store_dwordx2 v[200:201], v[52:53], off offset:64
	s_waitcnt vmcnt(11)
	v_lshlrev_b32_e32 v198, 16, v226
	v_and_b32_e32 v199, 0xffff0000, v226
	v_pk_fma_f32 v[48:49], v[48:49], v[198:199], v[166:167]
	v_lshlrev_b32_e32 v226, 16, v227
	v_and_b32_e32 v227, 0xffff0000, v227
	v_pk_fma_f32 v[50:51], v[50:51], v[226:227], v[168:169]
	s_nop 0
	v_bfe_u32 v198, v48, 16, 1
	v_add3_u32 v48, v48, v198, s33
	v_bfe_u32 v198, v49, 16, 1
	v_add3_u32 v49, v49, v198, s33
	v_bfe_u32 v198, v50, 16, 1
	v_add3_u32 v50, v50, v198, s33
	v_bfe_u32 v198, v51, 16, 1
	v_add3_u32 v51, v51, v198, s33
	v_perm_b32 v48, v49, v48, s96
	v_perm_b32 v49, v51, v50, s96
	global_store_dwordx2 v[200:201], v[48:49], off offset:96
	v_add_u32_e32 v114, 0x30000, v194
	v_lshl_add_u64 v[206:207], v[114:115], 0, s[4:5]
	global_load_dwordx4 v[126:129], v[206:207], off
	global_load_dwordx4 v[130:133], v[206:207], off offset:64
	global_load_dwordx4 v[156:159], v[206:207], off offset:128
	global_load_dwordx4 v[166:169], v[206:207], off offset:192
	v_add_u32_e32 v114, 0x40000, v194
	v_lshl_add_u64 v[206:207], v[114:115], 0, s[4:5]
	global_load_dwordx4 v[212:215], v[206:207], off
	global_load_dwordx4 v[216:219], v[206:207], off offset:64
	global_load_dwordx4 v[220:223], v[206:207], off offset:128
	global_load_dwordx4 v[224:227], v[206:207], off offset:192
	v_add_u32_e32 v114, 0x10000, v195
	v_lshl_add_u64 v[200:201], v[114:115], 0, s[6:7]
	s_waitcnt vmcnt(15)
	v_lshlrev_b32_e32 v198, 16, v202
	v_and_b32_e32 v199, 0xffff0000, v202
	v_pk_fma_f32 v[44:45], v[44:45], v[198:199], v[76:77]
	v_lshlrev_b32_e32 v202, 16, v203
	v_and_b32_e32 v203, 0xffff0000, v203
	v_pk_fma_f32 v[46:47], v[46:47], v[202:203], v[78:79]
	s_nop 0
	v_bfe_u32 v198, v44, 16, 1
	v_add3_u32 v44, v44, v198, s33
	v_bfe_u32 v198, v45, 16, 1
	v_add3_u32 v45, v45, v198, s33
	v_bfe_u32 v198, v46, 16, 1
	v_add3_u32 v46, v46, v198, s33
	v_bfe_u32 v198, v47, 16, 1
	v_add3_u32 v47, v47, v198, s33
	v_perm_b32 v44, v45, v44, s96
	v_perm_b32 v45, v47, v46, s96
	global_store_dwordx2 v[200:201], v[44:45], off
	s_waitcnt vmcnt(15)
	v_lshlrev_b32_e32 v198, 16, v210
	v_and_b32_e32 v199, 0xffff0000, v210
	v_pk_fma_f32 v[40:41], v[40:41], v[198:199], v[106:107]
	v_lshlrev_b32_e32 v210, 16, v211
	v_and_b32_e32 v211, 0xffff0000, v211
	v_pk_fma_f32 v[42:43], v[42:43], v[210:211], v[108:109]
	s_nop 0
	v_bfe_u32 v198, v40, 16, 1
	v_add3_u32 v40, v40, v198, s33
	v_bfe_u32 v198, v41, 16, 1
	v_add3_u32 v41, v41, v198, s33
	v_bfe_u32 v198, v42, 16, 1
	v_add3_u32 v42, v42, v198, s33
	v_bfe_u32 v198, v43, 16, 1
	v_add3_u32 v43, v43, v198, s33
	v_perm_b32 v40, v41, v40, s96
	v_perm_b32 v41, v43, v42, s96
	global_store_dwordx2 v[200:201], v[40:41], off offset:32
	s_waitcnt vmcnt(15)
	v_lshlrev_b32_e32 v198, 16, v230
	v_and_b32_e32 v199, 0xffff0000, v230
	v_pk_fma_f32 v[36:37], v[36:37], v[198:199], v[110:111]
	v_lshlrev_b32_e32 v230, 16, v231
	v_and_b32_e32 v231, 0xffff0000, v231
	v_pk_fma_f32 v[38:39], v[38:39], v[230:231], v[112:113]
	s_nop 0
	v_bfe_u32 v198, v36, 16, 1
	v_add3_u32 v36, v36, v198, s33
	v_bfe_u32 v198, v37, 16, 1
	v_add3_u32 v37, v37, v198, s33
	v_bfe_u32 v198, v38, 16, 1
	v_add3_u32 v38, v38, v198, s33
	v_bfe_u32 v198, v39, 16, 1
	v_add3_u32 v39, v39, v198, s33
	v_perm_b32 v36, v37, v36, s96
	v_perm_b32 v37, v39, v38, s96
	global_store_dwordx2 v[200:201], v[36:37], off offset:64
	s_waitcnt vmcnt(15)
	v_lshlrev_b32_e32 v198, 16, v232
	v_and_b32_e32 v199, 0xffff0000, v232
	v_pk_fma_f32 v[32:33], v[32:33], v[198:199], v[122:123]
	v_lshlrev_b32_e32 v232, 16, v233
	v_and_b32_e32 v233, 0xffff0000, v233
	v_pk_fma_f32 v[34:35], v[34:35], v[232:233], v[124:125]
	s_nop 0
	v_bfe_u32 v198, v32, 16, 1
	v_add3_u32 v32, v32, v198, s33
	v_bfe_u32 v198, v33, 16, 1
	v_add3_u32 v33, v33, v198, s33
	v_bfe_u32 v198, v34, 16, 1
	v_add3_u32 v34, v34, v198, s33
	v_bfe_u32 v198, v35, 16, 1
	v_add3_u32 v35, v35, v198, s33
	v_perm_b32 v32, v33, v32, s96
	v_perm_b32 v33, v35, v34, s96
	global_store_dwordx2 v[200:201], v[32:33], off offset:96
	v_add_u32_e32 v114, 0x18000, v195
	v_lshl_add_u64 v[200:201], v[114:115], 0, s[6:7]
	s_waitcnt vmcnt(11)
	v_lshlrev_b32_e32 v198, 16, v234
	v_and_b32_e32 v199, 0xffff0000, v234
	v_pk_fma_f32 v[28:29], v[28:29], v[198:199], v[126:127]
	v_lshlrev_b32_e32 v234, 16, v235
	v_and_b32_e32 v235, 0xffff0000, v235
	v_pk_fma_f32 v[30:31], v[30:31], v[234:235], v[128:129]
	s_nop 0
	v_bfe_u32 v198, v28, 16, 1
	v_add3_u32 v28, v28, v198, s33
	v_bfe_u32 v198, v29, 16, 1
	v_add3_u32 v29, v29, v198, s33
	v_bfe_u32 v198, v30, 16, 1
	v_add3_u32 v30, v30, v198, s33
	v_bfe_u32 v198, v31, 16, 1
	v_add3_u32 v31, v31, v198, s33
	v_perm_b32 v28, v29, v28, s96
	v_perm_b32 v29, v31, v30, s96
	global_store_dwordx2 v[200:201], v[28:29], off
	s_waitcnt vmcnt(11)
	v_lshlrev_b32_e32 v198, 16, v236
	v_and_b32_e32 v199, 0xffff0000, v236
	v_pk_fma_f32 v[24:25], v[24:25], v[198:199], v[130:131]
	v_lshlrev_b32_e32 v236, 16, v237
	v_and_b32_e32 v237, 0xffff0000, v237
	v_pk_fma_f32 v[26:27], v[26:27], v[236:237], v[132:133]
	s_nop 0
	v_bfe_u32 v198, v24, 16, 1
	v_add3_u32 v24, v24, v198, s33
	v_bfe_u32 v198, v25, 16, 1
	v_add3_u32 v25, v25, v198, s33
	v_bfe_u32 v198, v26, 16, 1
	v_add3_u32 v26, v26, v198, s33
	v_bfe_u32 v198, v27, 16, 1
	v_add3_u32 v27, v27, v198, s33
	v_perm_b32 v24, v25, v24, s96
	v_perm_b32 v25, v27, v26, s96
	global_store_dwordx2 v[200:201], v[24:25], off offset:32
	s_waitcnt vmcnt(11)
	v_lshlrev_b32_e32 v198, 16, v238
	v_and_b32_e32 v199, 0xffff0000, v238
	v_pk_fma_f32 v[20:21], v[20:21], v[198:199], v[156:157]
	v_lshlrev_b32_e32 v238, 16, v239
	v_and_b32_e32 v239, 0xffff0000, v239
	v_pk_fma_f32 v[22:23], v[22:23], v[238:239], v[158:159]
	s_nop 0
	v_bfe_u32 v198, v20, 16, 1
	v_add3_u32 v20, v20, v198, s33
	v_bfe_u32 v198, v21, 16, 1
	v_add3_u32 v21, v21, v198, s33
	v_bfe_u32 v198, v22, 16, 1
	v_add3_u32 v22, v22, v198, s33
	v_bfe_u32 v198, v23, 16, 1
	v_add3_u32 v23, v23, v198, s33
	v_perm_b32 v20, v21, v20, s96
	v_perm_b32 v21, v23, v22, s96
	global_store_dwordx2 v[200:201], v[20:21], off offset:64
	s_waitcnt vmcnt(11)
	v_lshlrev_b32_e32 v198, 16, v240
	v_and_b32_e32 v199, 0xffff0000, v240
	v_pk_fma_f32 v[16:17], v[16:17], v[198:199], v[166:167]
	v_lshlrev_b32_e32 v240, 16, v241
	v_and_b32_e32 v241, 0xffff0000, v241
	v_pk_fma_f32 v[18:19], v[18:19], v[240:241], v[168:169]
	s_nop 0
	v_bfe_u32 v198, v16, 16, 1
	v_add3_u32 v16, v16, v198, s33
	v_bfe_u32 v198, v17, 16, 1
	v_add3_u32 v17, v17, v198, s33
	v_bfe_u32 v198, v18, 16, 1
	v_add3_u32 v18, v18, v198, s33
	v_bfe_u32 v198, v19, 16, 1
	v_add3_u32 v19, v19, v198, s33
	v_perm_b32 v16, v17, v16, s96
	v_perm_b32 v17, v19, v18, s96
	global_store_dwordx2 v[200:201], v[16:17], off offset:96
	v_add_u32_e32 v114, 0x20000, v195
	v_lshl_add_u64 v[200:201], v[114:115], 0, s[6:7]
	s_waitcnt vmcnt(11)
	v_lshlrev_b32_e32 v198, 16, v242
	v_and_b32_e32 v199, 0xffff0000, v242
	v_pk_fma_f32 v[12:13], v[12:13], v[198:199], v[212:213]
	v_lshlrev_b32_e32 v242, 16, v243
	v_and_b32_e32 v243, 0xffff0000, v243
	v_pk_fma_f32 v[14:15], v[14:15], v[242:243], v[214:215]
	s_nop 0
	v_bfe_u32 v198, v12, 16, 1
	v_add3_u32 v12, v12, v198, s33
	v_bfe_u32 v198, v13, 16, 1
	v_add3_u32 v13, v13, v198, s33
	v_bfe_u32 v198, v14, 16, 1
	v_add3_u32 v14, v14, v198, s33
	v_bfe_u32 v198, v15, 16, 1
	v_add3_u32 v15, v15, v198, s33
	v_perm_b32 v12, v13, v12, s96
	v_perm_b32 v13, v15, v14, s96
	global_store_dwordx2 v[200:201], v[12:13], off
	s_waitcnt vmcnt(11)
	v_lshlrev_b32_e32 v198, 16, v244
	v_and_b32_e32 v199, 0xffff0000, v244
	v_pk_fma_f32 v[8:9], v[8:9], v[198:199], v[216:217]
	v_lshlrev_b32_e32 v244, 16, v245
	v_and_b32_e32 v245, 0xffff0000, v245
	v_pk_fma_f32 v[10:11], v[10:11], v[244:245], v[218:219]
	s_nop 0
	v_bfe_u32 v198, v8, 16, 1
	v_add3_u32 v8, v8, v198, s33
	v_bfe_u32 v198, v9, 16, 1
	v_add3_u32 v9, v9, v198, s33
	v_bfe_u32 v198, v10, 16, 1
	v_add3_u32 v10, v10, v198, s33
	v_bfe_u32 v198, v11, 16, 1
	v_add3_u32 v11, v11, v198, s33
	v_perm_b32 v8, v9, v8, s96
	v_perm_b32 v9, v11, v10, s96
	global_store_dwordx2 v[200:201], v[8:9], off offset:32
	s_waitcnt vmcnt(11)
	v_lshlrev_b32_e32 v198, 16, v246
	v_and_b32_e32 v199, 0xffff0000, v246
	v_pk_fma_f32 v[4:5], v[4:5], v[198:199], v[220:221]
	v_lshlrev_b32_e32 v246, 16, v247
	v_and_b32_e32 v247, 0xffff0000, v247
	v_pk_fma_f32 v[6:7], v[6:7], v[246:247], v[222:223]
	s_nop 0
	v_bfe_u32 v198, v4, 16, 1
	v_add3_u32 v4, v4, v198, s33
	v_bfe_u32 v198, v5, 16, 1
	v_add3_u32 v5, v5, v198, s33
	v_bfe_u32 v198, v6, 16, 1
	v_add3_u32 v6, v6, v198, s33
	v_bfe_u32 v198, v7, 16, 1
	v_add3_u32 v7, v7, v198, s33
	v_perm_b32 v4, v5, v4, s96
	v_perm_b32 v5, v7, v6, s96
	global_store_dwordx2 v[200:201], v[4:5], off offset:64
	s_waitcnt vmcnt(11)
	v_lshlrev_b32_e32 v198, 16, v248
	v_and_b32_e32 v199, 0xffff0000, v248
	v_pk_fma_f32 v[0:1], v[0:1], v[198:199], v[224:225]
	v_lshlrev_b32_e32 v248, 16, v249
	v_and_b32_e32 v249, 0xffff0000, v249
	v_pk_fma_f32 v[2:3], v[2:3], v[248:249], v[226:227]
	s_nop 0
	v_bfe_u32 v198, v0, 16, 1
	v_add3_u32 v0, v0, v198, s33
	v_bfe_u32 v198, v1, 16, 1
	v_add3_u32 v1, v1, v198, s33
	v_bfe_u32 v198, v2, 16, 1
	v_add3_u32 v2, v2, v198, s33
	v_bfe_u32 v198, v3, 16, 1
	v_add3_u32 v3, v3, v198, s33
	v_perm_b32 v0, v1, v0, s96
	v_perm_b32 v1, v3, v2, s96
	global_store_dwordx2 v[200:201], v[0:1], off offset:96
	s_mov_b32 s35, 0
	s_movk_i32 s8, 0x50
	s_movk_i32 s10, 0x3200
	s_mov_b64 s[12:13], 0x2800
